# v34 = v31 + w_in (EPI-0) epilogue deferred under the next tile prologue loads (packed acc kept in v190..253, masked last n-tile, flush at tile-loop exit)
# baseline (speedup 1.0000x reference)
.Lw_flush_0:
	s_cmp_eq_u32 s45, 0
	s_cbranch_scc1 .LBB0_293
	v_and_b32_e32 v3, 15, v182
	v_cmp_gt_u32_e64 s[42:43], 4, v3
	s_cmp_eq_u32 s45, 2
	s_cselect_b64 s[42:43], s[42:43], -1
	v_lshrrev_b32_e32 v4, 4, v182
	v_mul_u32_u24_e32 v2, 0x1240, v4
	v_lshl_add_u32 v2, v3, 4, v2
	v_mul_u32_u24_e32 v1, 0x110, v4
	v_lshl_add_u32 v1, v3, 4, v1
	v_lshrrev_b32_e32 v3, 7, v182
	v_bfe_u32 v4, v182, 5, 1
	v_lshlrev_b32_e32 v3, 6, v3
	v_lshl_or_b32 v3, v4, 2, v3
	v_mul_u32_u24_e32 v3, 136, v3
	v_and_b32_e32 v4, 0x5f, v182
	v_add_lshl_u32 v0, v3, v4, 1
	s_barrier
	ds_write_b16 v0, v190
	ds_write_b16_d16_hi v0, v190 offset:272
	ds_write_b16 v0, v191 offset:544
	ds_write_b16_d16_hi v0, v191 offset:816
	ds_write_b16 v0, v192 offset:2176
	ds_write_b16_d16_hi v0, v192 offset:2448
	ds_write_b16 v0, v193 offset:2720
	ds_write_b16_d16_hi v0, v193 offset:2992
	ds_write_b16 v0, v194 offset:4352
	ds_write_b16_d16_hi v0, v194 offset:4624
	ds_write_b16 v0, v195 offset:4896
	ds_write_b16_d16_hi v0, v195 offset:5168
	ds_write_b16 v0, v196 offset:6528
	ds_write_b16_d16_hi v0, v196 offset:6800
	ds_write_b16 v0, v197 offset:7072
	ds_write_b16_d16_hi v0, v197 offset:7344
	ds_write_b16 v0, v198 offset:64
	ds_write_b16_d16_hi v0, v198 offset:336
	ds_write_b16 v0, v199 offset:608
	ds_write_b16_d16_hi v0, v199 offset:880
	ds_write_b16 v0, v200 offset:2240
	ds_write_b16_d16_hi v0, v200 offset:2512
	ds_write_b16 v0, v201 offset:2784
	ds_write_b16_d16_hi v0, v201 offset:3056
	ds_write_b16 v0, v202 offset:4416
	ds_write_b16_d16_hi v0, v202 offset:4688
	ds_write_b16 v0, v203 offset:4960
	ds_write_b16_d16_hi v0, v203 offset:5232
	ds_write_b16 v0, v204 offset:6592
	ds_write_b16_d16_hi v0, v204 offset:6864
	ds_write_b16 v0, v205 offset:7136
	ds_write_b16_d16_hi v0, v205 offset:7408
	ds_write_b16 v0, v206 offset:8704
	ds_write_b16_d16_hi v0, v206 offset:8976
	ds_write_b16 v0, v207 offset:9248
	ds_write_b16_d16_hi v0, v207 offset:9520
	ds_write_b16 v0, v208 offset:10880
	ds_write_b16_d16_hi v0, v208 offset:11152
	ds_write_b16 v0, v209 offset:11424
	ds_write_b16_d16_hi v0, v209 offset:11696
	ds_write_b16 v0, v210 offset:13056
	ds_write_b16_d16_hi v0, v210 offset:13328
	ds_write_b16 v0, v211 offset:13600
	ds_write_b16_d16_hi v0, v211 offset:13872
	ds_write_b16 v0, v212 offset:15232
	ds_write_b16_d16_hi v0, v212 offset:15504
	ds_write_b16 v0, v213 offset:15776
	ds_write_b16_d16_hi v0, v213 offset:16048
	ds_write_b16 v0, v214 offset:8768
	ds_write_b16_d16_hi v0, v214 offset:9040
	ds_write_b16 v0, v215 offset:9312
	ds_write_b16_d16_hi v0, v215 offset:9584
	ds_write_b16 v0, v216 offset:10944
	ds_write_b16_d16_hi v0, v216 offset:11216
	ds_write_b16 v0, v217 offset:11488
	ds_write_b16_d16_hi v0, v217 offset:11760
	ds_write_b16 v0, v218 offset:13120
	ds_write_b16_d16_hi v0, v218 offset:13392
	ds_write_b16 v0, v219 offset:13664
	ds_write_b16_d16_hi v0, v219 offset:13936
	ds_write_b16 v0, v220 offset:15296
	ds_write_b16_d16_hi v0, v220 offset:15568
	ds_write_b16 v0, v221 offset:15840
	ds_write_b16_d16_hi v0, v221 offset:16112
	s_waitcnt lgkmcnt(0)
	s_barrier
	ds_read_b128 v[8:11], v1
	ds_read_b128 v[12:15], v1 offset:4352
	ds_read_b128 v[16:19], v1 offset:8704
	ds_read_b128 v[20:23], v1 offset:13056
	ds_read_b128 v[24:27], v1 offset:17408
	ds_read_b128 v[28:31], v1 offset:21760
	ds_read_b128 v[32:35], v1 offset:26112
	ds_read_b128 v[36:39], v1 offset:30464
	s_and_b64 exec, exec, s[42:43]
	s_add_u32 s40, s46, 0x0
	s_addc_u32 s41, s47, 0
	s_waitcnt lgkmcnt(7)
	global_store_dwordx4 v2, v[8:11], s[40:41]
	s_add_u32 s40, s46, 0x12400
	s_addc_u32 s41, s47, 0
	s_waitcnt lgkmcnt(6)
	global_store_dwordx4 v2, v[12:15], s[40:41]
	s_add_u32 s40, s46, 0x24800
	s_addc_u32 s41, s47, 0
	s_waitcnt lgkmcnt(5)
	global_store_dwordx4 v2, v[16:19], s[40:41]
	s_add_u32 s40, s46, 0x36c00
	s_addc_u32 s41, s47, 0
	s_waitcnt lgkmcnt(4)
	global_store_dwordx4 v2, v[20:23], s[40:41]
	s_add_u32 s40, s46, 0x92000
	s_addc_u32 s41, s47, 0
	s_waitcnt lgkmcnt(3)
	global_store_dwordx4 v2, v[24:27], s[40:41]
	s_add_u32 s40, s46, 0xa4400
	s_addc_u32 s41, s47, 0
	s_waitcnt lgkmcnt(2)
	global_store_dwordx4 v2, v[28:31], s[40:41]
	s_add_u32 s40, s46, 0xb6800
	s_addc_u32 s41, s47, 0
	s_waitcnt lgkmcnt(1)
	global_store_dwordx4 v2, v[32:35], s[40:41]
	s_add_u32 s40, s46, 0xc8c00
	s_addc_u32 s41, s47, 0
	s_waitcnt lgkmcnt(0)
	global_store_dwordx4 v2, v[36:39], s[40:41]
	s_mov_b64 exec, -1
	s_barrier
	ds_write_b16 v0, v222
	ds_write_b16_d16_hi v0, v222 offset:272
	ds_write_b16 v0, v223 offset:544
	ds_write_b16_d16_hi v0, v223 offset:816
	ds_write_b16 v0, v224 offset:2176
	ds_write_b16_d16_hi v0, v224 offset:2448
	ds_write_b16 v0, v225 offset:2720
	ds_write_b16_d16_hi v0, v225 offset:2992
	ds_write_b16 v0, v226 offset:4352
	ds_write_b16_d16_hi v0, v226 offset:4624
	ds_write_b16 v0, v227 offset:4896
	ds_write_b16_d16_hi v0, v227 offset:5168
	ds_write_b16 v0, v228 offset:6528
	ds_write_b16_d16_hi v0, v228 offset:6800
	ds_write_b16 v0, v229 offset:7072
	ds_write_b16_d16_hi v0, v229 offset:7344
	ds_write_b16 v0, v230 offset:64
	ds_write_b16_d16_hi v0, v230 offset:336
	ds_write_b16 v0, v231 offset:608
	ds_write_b16_d16_hi v0, v231 offset:880
	ds_write_b16 v0, v232 offset:2240
	ds_write_b16_d16_hi v0, v232 offset:2512
	ds_write_b16 v0, v233 offset:2784
	ds_write_b16_d16_hi v0, v233 offset:3056
	ds_write_b16 v0, v234 offset:4416
	ds_write_b16_d16_hi v0, v234 offset:4688
	ds_write_b16 v0, v235 offset:4960
	ds_write_b16_d16_hi v0, v235 offset:5232
	ds_write_b16 v0, v236 offset:6592
	ds_write_b16_d16_hi v0, v236 offset:6864
	ds_write_b16 v0, v237 offset:7136
	ds_write_b16_d16_hi v0, v237 offset:7408
	ds_write_b16 v0, v238 offset:8704
	ds_write_b16_d16_hi v0, v238 offset:8976
	ds_write_b16 v0, v239 offset:9248
	ds_write_b16_d16_hi v0, v239 offset:9520
	ds_write_b16 v0, v240 offset:10880
	ds_write_b16_d16_hi v0, v240 offset:11152
	ds_write_b16 v0, v241 offset:11424
	ds_write_b16_d16_hi v0, v241 offset:11696
	ds_write_b16 v0, v242 offset:13056
	ds_write_b16_d16_hi v0, v242 offset:13328
	ds_write_b16 v0, v243 offset:13600
	ds_write_b16_d16_hi v0, v243 offset:13872
	ds_write_b16 v0, v244 offset:15232
	ds_write_b16_d16_hi v0, v244 offset:15504
	ds_write_b16 v0, v245 offset:15776
	ds_write_b16_d16_hi v0, v245 offset:16048
	ds_write_b16 v0, v246 offset:8768
	ds_write_b16_d16_hi v0, v246 offset:9040
	ds_write_b16 v0, v247 offset:9312
	ds_write_b16_d16_hi v0, v247 offset:9584
	ds_write_b16 v0, v248 offset:10944
	ds_write_b16_d16_hi v0, v248 offset:11216
	ds_write_b16 v0, v249 offset:11488
	ds_write_b16_d16_hi v0, v249 offset:11760
	ds_write_b16 v0, v250 offset:13120
	ds_write_b16_d16_hi v0, v250 offset:13392
	ds_write_b16 v0, v251 offset:13664
	ds_write_b16_d16_hi v0, v251 offset:13936
	ds_write_b16 v0, v252 offset:15296
	ds_write_b16_d16_hi v0, v252 offset:15568
	ds_write_b16 v0, v253 offset:15840
	ds_write_b16_d16_hi v0, v253 offset:16112
	s_waitcnt lgkmcnt(0)
	s_barrier
	ds_read_b128 v[8:11], v1
	ds_read_b128 v[12:15], v1 offset:4352
	ds_read_b128 v[16:19], v1 offset:8704
	ds_read_b128 v[20:23], v1 offset:13056
	ds_read_b128 v[24:27], v1 offset:17408
	ds_read_b128 v[28:31], v1 offset:21760
	ds_read_b128 v[32:35], v1 offset:26112
	ds_read_b128 v[36:39], v1 offset:30464
	s_and_b64 exec, exec, s[42:43]
	s_add_u32 s40, s46, 0x49000
	s_addc_u32 s41, s47, 0
	s_waitcnt lgkmcnt(7)
	global_store_dwordx4 v2, v[8:11], s[40:41]
	s_add_u32 s40, s46, 0x5b400
	s_addc_u32 s41, s47, 0
	s_waitcnt lgkmcnt(6)
	global_store_dwordx4 v2, v[12:15], s[40:41]
	s_add_u32 s40, s46, 0x6d800
	s_addc_u32 s41, s47, 0
	s_waitcnt lgkmcnt(5)
	global_store_dwordx4 v2, v[16:19], s[40:41]
	s_add_u32 s40, s46, 0x7fc00
	s_addc_u32 s41, s47, 0
	s_waitcnt lgkmcnt(4)
	global_store_dwordx4 v2, v[20:23], s[40:41]
	s_add_u32 s40, s46, 0xdb000
	s_addc_u32 s41, s47, 0
	s_waitcnt lgkmcnt(3)
	global_store_dwordx4 v2, v[24:27], s[40:41]
	s_add_u32 s40, s46, 0xed400
	s_addc_u32 s41, s47, 0
	s_waitcnt lgkmcnt(2)
	global_store_dwordx4 v2, v[28:31], s[40:41]
	s_add_u32 s40, s46, 0xff800
	s_addc_u32 s41, s47, 0
	s_waitcnt lgkmcnt(1)
	global_store_dwordx4 v2, v[32:35], s[40:41]
	s_add_u32 s40, s46, 0x111c00
	s_addc_u32 s41, s47, 0
	s_waitcnt lgkmcnt(0)
	global_store_dwordx4 v2, v[36:39], s[40:41]
	s_mov_b64 exec, -1
	s_mov_b32 s45, 0

.LBB0_298:
	s_and_b64 vcc, exec, s[4:5]
	s_cbranch_vccnz .LBB0_293
	s_mov_b32 s55, s18
	s_mov_b32 s45, 0
	s_branch .LBB0_301

.LBB0_301:
	s_mul_hi_u32 s0, s55, s25
	s_mul_i32 s1, s0, s20
	s_sub_i32 s1, s55, s1
	s_add_i32 s8, s0, 1
	s_sub_i32 s12, s1, s20
	s_cmp_ge_u32 s1, s20
	s_cselect_b32 s0, s8, s0
	s_cselect_b32 s1, s12, s1
	s_add_i32 s8, s0, 1
	s_cmp_ge_u32 s1, s20
	s_cselect_b32 s0, s8, s0
	s_add_i32 s1, s0, s23
	s_mul_i32 s0, s0, s20
	s_sub_i32 s0, s55, s0
	s_add_i32 s0, s0, s19
	s_lshl_b32 s12, s1, 8
	s_lshl_b32 s8, s0, 7
	s_mov_b64 s[0:1], s[30:31]
	v_mov_b32_e32 v0, v177
	s_mov_b32 s13, s9
	v_mbcnt_lo_u32_b32 v0, -1, v0
	v_mbcnt_hi_u32_b32 v0, -1, v0
	v_add_u32_e32 v182, s33, v0
	s_lshl_b64 s[16:17], s[12:13], 11
	v_ashrrev_i32_e32 v0, 3, v182
	v_lshlrev_b32_e32 v1, 3, v182
	s_add_u32 s56, s14, s16
	v_and_b32_e32 v6, 56, v1
	v_lshlrev_b32_e32 v1, 11, v0
	s_addc_u32 s57, s15, s17
	v_lshl_or_b32 v176, v6, 1, v1
	v_mul_lo_u32 v7, v0, s21
	v_lshl_add_u64 v[0:1], s[56:57], 0, v[176:177]
	v_add_co_u32_e32 v2, vcc, s26, v0
	s_lshl_b64 s[58:59], s[8:9], 11
	s_nop 0
	v_addc_co_u32_e32 v3, vcc, 0, v1, vcc
	v_add_co_u32_e32 v4, vcc, s27, v0
	s_add_u32 s58, s30, s58
	s_nop 0
	v_addc_co_u32_e32 v5, vcc, 0, v1, vcc
	global_load_dwordx4 v[128:131], v[2:3], off
	global_load_dwordx4 v[132:135], v[4:5], off
	v_add_co_u32_e32 v2, vcc, s34, v0
	s_addc_u32 s59, s31, s59
	s_nop 0
	v_addc_co_u32_e32 v3, vcc, 0, v1, vcc
	v_add_co_u32_e32 v4, vcc, s35, v0
	v_lshl_add_u64 v[178:179], s[58:59], 0, v[176:177]
	s_nop 0
	v_addc_co_u32_e32 v5, vcc, 0, v1, vcc
	global_load_dwordx4 v[136:139], v[2:3], off
	global_load_dwordx4 v[144:147], v[4:5], off
	v_add_co_u32_e32 v2, vcc, s36, v0
	v_bfe_u32 v185, v182, 6, 1
	s_nop 0
	v_addc_co_u32_e32 v3, vcc, 0, v1, vcc
	v_add_co_u32_e32 v4, vcc, s37, v0
	v_and_b32_e32 v184, 31, v182
	s_nop 0
	v_addc_co_u32_e32 v5, vcc, 0, v1, vcc
	v_add_co_u32_e32 v0, vcc, s38, v0
	global_load_dwordx4 v[148:151], v[2:3], off
	global_load_dwordx4 v[152:155], v[4:5], off
	v_addc_co_u32_e32 v1, vcc, 0, v1, vcc
	v_add_co_u32_e32 v2, vcc, s26, v178
	global_load_dwordx4 v[164:167], v176, s[56:57]
	global_load_dwordx4 v[140:143], v176, s[58:59]
	v_addc_co_u32_e32 v3, vcc, 0, v179, vcc
	global_load_dwordx4 v[156:159], v[0:1], off
	global_load_dwordx4 v[160:163], v[2:3], off
	v_add_co_u32_e32 v0, vcc, s27, v178
	v_bfe_u32 v186, v182, 5, 1
	s_nop 0
	v_addc_co_u32_e32 v1, vcc, 0, v179, vcc
	v_add_co_u32_e32 v2, vcc, s34, v178
	s_add_u32 s16, s30, s16
	s_nop 0
	v_addc_co_u32_e32 v3, vcc, 0, v179, vcc
	global_load_dwordx4 v[168:171], v[0:1], off
	global_load_dwordx4 v[172:175], v[2:3], off
	v_and_b32_e32 v0, 0xfffff9f, v182
	v_lshl_or_b32 v2, v185, 6, v184
	v_mul_lo_u32 v3, v0, s39
	v_or_b32_e32 v0, 0x60, v182
	v_lshlrev_b32_e32 v1, 4, v186
	v_mul_lo_u32 v4, v0, s39
	v_mul_u32_u24_e32 v2, 0x90, v2
	s_addc_u32 s17, s31, s17
	v_mov_b32_e32 v0, 0
	v_add_lshl_u32 v189, v7, v6, 1
	v_lshl_add_u64 v[180:181], s[16:17], 0, v[176:177]
	s_mov_b64 s[16:17], 0
	v_add_u32_e32 v188, v1, v3
	v_add_u32_e32 v187, v1, v4
	v_add_u32_e32 v176, v1, v2
	v_mov_b32_e32 v1, v0
	v_mov_b32_e32 v2, v0
	v_mov_b32_e32 v3, v0
	v_mov_b32_e32 v4, v0
	v_mov_b32_e32 v5, v0
	v_mov_b32_e32 v6, v0
	v_mov_b32_e32 v7, v0
	v_mov_b32_e32 v8, v0
	v_mov_b32_e32 v9, v0
	v_mov_b32_e32 v10, v0
	v_mov_b32_e32 v11, v0
	v_mov_b32_e32 v12, v0
	v_mov_b32_e32 v13, v0
	v_mov_b32_e32 v14, v0
	v_mov_b32_e32 v15, v0
	v_mov_b32_e32 v16, v0
	v_mov_b32_e32 v17, v0
	v_mov_b32_e32 v18, v0
	v_mov_b32_e32 v19, v0
	v_mov_b32_e32 v20, v0
	v_mov_b32_e32 v21, v0
	v_mov_b32_e32 v22, v0
	v_mov_b32_e32 v23, v0
	v_mov_b32_e32 v24, v0
	v_mov_b32_e32 v25, v0
	v_mov_b32_e32 v26, v0
	v_mov_b32_e32 v27, v0
	v_mov_b32_e32 v28, v0
	v_mov_b32_e32 v29, v0
	v_mov_b32_e32 v30, v0
	v_mov_b32_e32 v31, v0
	v_mov_b32_e32 v32, v0
	v_mov_b32_e32 v33, v0
	v_mov_b32_e32 v34, v0
	v_mov_b32_e32 v35, v0
	v_mov_b32_e32 v36, v0
	v_mov_b32_e32 v37, v0
	v_mov_b32_e32 v38, v0
	v_mov_b32_e32 v39, v0
	v_mov_b32_e32 v40, v0
	v_mov_b32_e32 v41, v0
	v_mov_b32_e32 v42, v0
	v_mov_b32_e32 v43, v0
	v_mov_b32_e32 v44, v0
	v_mov_b32_e32 v45, v0
	v_mov_b32_e32 v46, v0
	v_mov_b32_e32 v47, v0
	v_mov_b32_e32 v48, v0
	v_mov_b32_e32 v49, v0
	v_mov_b32_e32 v50, v0
	v_mov_b32_e32 v51, v0
	v_mov_b32_e32 v52, v0
	v_mov_b32_e32 v53, v0
	v_mov_b32_e32 v54, v0
	v_mov_b32_e32 v55, v0
	v_mov_b32_e32 v56, v0
	v_mov_b32_e32 v57, v0
	v_mov_b32_e32 v58, v0
	v_mov_b32_e32 v59, v0
	v_mov_b32_e32 v60, v0
	v_mov_b32_e32 v61, v0
	v_mov_b32_e32 v62, v0
	v_mov_b32_e32 v63, v0
	v_mov_b32_e32 v64, v0
	v_mov_b32_e32 v65, v0
	v_mov_b32_e32 v66, v0
	v_mov_b32_e32 v67, v0
	v_mov_b32_e32 v68, v0
	v_mov_b32_e32 v69, v0
	v_mov_b32_e32 v70, v0
	v_mov_b32_e32 v71, v0
	v_mov_b32_e32 v72, v0
	v_mov_b32_e32 v73, v0
	v_mov_b32_e32 v74, v0
	v_mov_b32_e32 v75, v0
	v_mov_b32_e32 v76, v0
	v_mov_b32_e32 v77, v0
	v_mov_b32_e32 v78, v0
	v_mov_b32_e32 v79, v0
	v_mov_b32_e32 v80, v0
	v_mov_b32_e32 v81, v0
	v_mov_b32_e32 v82, v0
	v_mov_b32_e32 v83, v0
	v_mov_b32_e32 v84, v0
	v_mov_b32_e32 v85, v0
	v_mov_b32_e32 v86, v0
	v_mov_b32_e32 v87, v0
	v_mov_b32_e32 v88, v0
	v_mov_b32_e32 v89, v0
	v_mov_b32_e32 v90, v0
	v_mov_b32_e32 v91, v0
	v_mov_b32_e32 v92, v0
	v_mov_b32_e32 v93, v0
	v_mov_b32_e32 v94, v0
	v_mov_b32_e32 v95, v0
	v_mov_b32_e32 v96, v0
	v_mov_b32_e32 v97, v0
	v_mov_b32_e32 v98, v0
	v_mov_b32_e32 v99, v0
	v_mov_b32_e32 v100, v0
	v_mov_b32_e32 v101, v0
	v_mov_b32_e32 v102, v0
	v_mov_b32_e32 v103, v0
	v_mov_b32_e32 v104, v0
	v_mov_b32_e32 v105, v0
	v_mov_b32_e32 v106, v0
	v_mov_b32_e32 v107, v0
	v_mov_b32_e32 v108, v0
	v_mov_b32_e32 v109, v0
	v_mov_b32_e32 v110, v0
	v_mov_b32_e32 v111, v0
	v_mov_b32_e32 v112, v0
	v_mov_b32_e32 v113, v0
	v_mov_b32_e32 v114, v0
	v_mov_b32_e32 v115, v0
	v_mov_b32_e32 v116, v0
	v_mov_b32_e32 v117, v0
	v_mov_b32_e32 v118, v0
	v_mov_b32_e32 v119, v0
	v_mov_b32_e32 v120, v0
	v_mov_b32_e32 v121, v0
	v_mov_b32_e32 v122, v0
	v_mov_b32_e32 v123, v0
	v_mov_b32_e32 v124, v0
	v_mov_b32_e32 v125, v0
	v_mov_b32_e32 v126, v0
	v_mov_b32_e32 v127, v0
	s_cmp_eq_u32 s45, 0
	s_cbranch_scc1 .Lv5_a_0
	v_and_b32_e32 v3, 15, v182
	v_cmp_gt_u32_e64 s[42:43], 4, v3
	s_cmp_eq_u32 s45, 2
	s_cselect_b64 s[42:43], s[42:43], -1
	v_lshrrev_b32_e32 v4, 4, v182
	v_mul_u32_u24_e32 v2, 0x1240, v4
	v_lshl_add_u32 v2, v3, 4, v2
	v_mul_u32_u24_e32 v1, 0x110, v4
	v_lshl_add_u32 v1, v3, 4, v1
	v_lshrrev_b32_e32 v3, 7, v182
	v_bfe_u32 v4, v182, 5, 1
	v_lshlrev_b32_e32 v3, 6, v3
	v_lshl_or_b32 v3, v4, 2, v3
	v_mul_u32_u24_e32 v3, 136, v3
	v_and_b32_e32 v4, 0x5f, v182
	v_add_lshl_u32 v0, v3, v4, 1
	s_barrier
	ds_write_b16 v0, v190
	ds_write_b16_d16_hi v0, v190 offset:272
	ds_write_b16 v0, v191 offset:544
	ds_write_b16_d16_hi v0, v191 offset:816
	ds_write_b16 v0, v192 offset:2176
	ds_write_b16_d16_hi v0, v192 offset:2448
	ds_write_b16 v0, v193 offset:2720
	ds_write_b16_d16_hi v0, v193 offset:2992
	ds_write_b16 v0, v194 offset:4352
	ds_write_b16_d16_hi v0, v194 offset:4624
	ds_write_b16 v0, v195 offset:4896
	ds_write_b16_d16_hi v0, v195 offset:5168
	ds_write_b16 v0, v196 offset:6528
	ds_write_b16_d16_hi v0, v196 offset:6800
	ds_write_b16 v0, v197 offset:7072
	ds_write_b16_d16_hi v0, v197 offset:7344
	ds_write_b16 v0, v198 offset:64
	ds_write_b16_d16_hi v0, v198 offset:336
	ds_write_b16 v0, v199 offset:608
	ds_write_b16_d16_hi v0, v199 offset:880
	ds_write_b16 v0, v200 offset:2240
	ds_write_b16_d16_hi v0, v200 offset:2512
	ds_write_b16 v0, v201 offset:2784
	ds_write_b16_d16_hi v0, v201 offset:3056
	ds_write_b16 v0, v202 offset:4416
	ds_write_b16_d16_hi v0, v202 offset:4688
	ds_write_b16 v0, v203 offset:4960
	ds_write_b16_d16_hi v0, v203 offset:5232
	ds_write_b16 v0, v204 offset:6592
	ds_write_b16_d16_hi v0, v204 offset:6864
	ds_write_b16 v0, v205 offset:7136
	ds_write_b16_d16_hi v0, v205 offset:7408
	ds_write_b16 v0, v206 offset:8704
	ds_write_b16_d16_hi v0, v206 offset:8976
	ds_write_b16 v0, v207 offset:9248
	ds_write_b16_d16_hi v0, v207 offset:9520
	ds_write_b16 v0, v208 offset:10880
	ds_write_b16_d16_hi v0, v208 offset:11152
	ds_write_b16 v0, v209 offset:11424
	ds_write_b16_d16_hi v0, v209 offset:11696
	ds_write_b16 v0, v210 offset:13056
	ds_write_b16_d16_hi v0, v210 offset:13328
	ds_write_b16 v0, v211 offset:13600
	ds_write_b16_d16_hi v0, v211 offset:13872
	ds_write_b16 v0, v212 offset:15232
	ds_write_b16_d16_hi v0, v212 offset:15504
	ds_write_b16 v0, v213 offset:15776
	ds_write_b16_d16_hi v0, v213 offset:16048
	ds_write_b16 v0, v214 offset:8768
	ds_write_b16_d16_hi v0, v214 offset:9040
	ds_write_b16 v0, v215 offset:9312
	ds_write_b16_d16_hi v0, v215 offset:9584
	ds_write_b16 v0, v216 offset:10944
	ds_write_b16_d16_hi v0, v216 offset:11216
	ds_write_b16 v0, v217 offset:11488
	ds_write_b16_d16_hi v0, v217 offset:11760
	ds_write_b16 v0, v218 offset:13120
	ds_write_b16_d16_hi v0, v218 offset:13392
	ds_write_b16 v0, v219 offset:13664
	ds_write_b16_d16_hi v0, v219 offset:13936
	ds_write_b16 v0, v220 offset:15296
	ds_write_b16_d16_hi v0, v220 offset:15568
	ds_write_b16 v0, v221 offset:15840
	ds_write_b16_d16_hi v0, v221 offset:16112
	s_waitcnt lgkmcnt(0)
	s_barrier
	ds_read_b128 v[8:11], v1
	ds_read_b128 v[12:15], v1 offset:4352
	ds_read_b128 v[16:19], v1 offset:8704
	ds_read_b128 v[20:23], v1 offset:13056
	ds_read_b128 v[24:27], v1 offset:17408
	ds_read_b128 v[28:31], v1 offset:21760
	ds_read_b128 v[32:35], v1 offset:26112
	ds_read_b128 v[36:39], v1 offset:30464
	s_and_b64 exec, exec, s[42:43]
	s_add_u32 s40, s46, 0x0
	s_addc_u32 s41, s47, 0
	s_waitcnt lgkmcnt(7)
	global_store_dwordx4 v2, v[8:11], s[40:41]
	s_add_u32 s40, s46, 0x12400
	s_addc_u32 s41, s47, 0
	s_waitcnt lgkmcnt(6)
	global_store_dwordx4 v2, v[12:15], s[40:41]
	s_add_u32 s40, s46, 0x24800
	s_addc_u32 s41, s47, 0
	s_waitcnt lgkmcnt(5)
	global_store_dwordx4 v2, v[16:19], s[40:41]
	s_add_u32 s40, s46, 0x36c00
	s_addc_u32 s41, s47, 0
	s_waitcnt lgkmcnt(4)
	global_store_dwordx4 v2, v[20:23], s[40:41]
	s_add_u32 s40, s46, 0x92000
	s_addc_u32 s41, s47, 0
	s_waitcnt lgkmcnt(3)
	global_store_dwordx4 v2, v[24:27], s[40:41]
	s_add_u32 s40, s46, 0xa4400
	s_addc_u32 s41, s47, 0
	s_waitcnt lgkmcnt(2)
	global_store_dwordx4 v2, v[28:31], s[40:41]
	s_add_u32 s40, s46, 0xb6800
	s_addc_u32 s41, s47, 0
	s_waitcnt lgkmcnt(1)
	global_store_dwordx4 v2, v[32:35], s[40:41]
	s_add_u32 s40, s46, 0xc8c00
	s_addc_u32 s41, s47, 0
	s_waitcnt lgkmcnt(0)
	global_store_dwordx4 v2, v[36:39], s[40:41]
	s_mov_b64 exec, -1
	s_barrier
	ds_write_b16 v0, v222
	ds_write_b16_d16_hi v0, v222 offset:272
	ds_write_b16 v0, v223 offset:544
	ds_write_b16_d16_hi v0, v223 offset:816
	ds_write_b16 v0, v224 offset:2176
	ds_write_b16_d16_hi v0, v224 offset:2448
	ds_write_b16 v0, v225 offset:2720
	ds_write_b16_d16_hi v0, v225 offset:2992
	ds_write_b16 v0, v226 offset:4352
	ds_write_b16_d16_hi v0, v226 offset:4624
	ds_write_b16 v0, v227 offset:4896
	ds_write_b16_d16_hi v0, v227 offset:5168
	ds_write_b16 v0, v228 offset:6528
	ds_write_b16_d16_hi v0, v228 offset:6800
	ds_write_b16 v0, v229 offset:7072
	ds_write_b16_d16_hi v0, v229 offset:7344
	ds_write_b16 v0, v230 offset:64
	ds_write_b16_d16_hi v0, v230 offset:336
	ds_write_b16 v0, v231 offset:608
	ds_write_b16_d16_hi v0, v231 offset:880
	ds_write_b16 v0, v232 offset:2240
	ds_write_b16_d16_hi v0, v232 offset:2512
	ds_write_b16 v0, v233 offset:2784
	ds_write_b16_d16_hi v0, v233 offset:3056
	ds_write_b16 v0, v234 offset:4416
	ds_write_b16_d16_hi v0, v234 offset:4688
	ds_write_b16 v0, v235 offset:4960
	ds_write_b16_d16_hi v0, v235 offset:5232
	ds_write_b16 v0, v236 offset:6592
	ds_write_b16_d16_hi v0, v236 offset:6864
	ds_write_b16 v0, v237 offset:7136
	ds_write_b16_d16_hi v0, v237 offset:7408
	ds_write_b16 v0, v238 offset:8704
	ds_write_b16_d16_hi v0, v238 offset:8976
	ds_write_b16 v0, v239 offset:9248
	ds_write_b16_d16_hi v0, v239 offset:9520
	ds_write_b16 v0, v240 offset:10880
	ds_write_b16_d16_hi v0, v240 offset:11152
	ds_write_b16 v0, v241 offset:11424
	ds_write_b16_d16_hi v0, v241 offset:11696
	ds_write_b16 v0, v242 offset:13056
	ds_write_b16_d16_hi v0, v242 offset:13328
	ds_write_b16 v0, v243 offset:13600
	ds_write_b16_d16_hi v0, v243 offset:13872
	ds_write_b16 v0, v244 offset:15232
	ds_write_b16_d16_hi v0, v244 offset:15504
	ds_write_b16 v0, v245 offset:15776
	ds_write_b16_d16_hi v0, v245 offset:16048
	ds_write_b16 v0, v246 offset:8768
	ds_write_b16_d16_hi v0, v246 offset:9040
	ds_write_b16 v0, v247 offset:9312
	ds_write_b16_d16_hi v0, v247 offset:9584
	ds_write_b16 v0, v248 offset:10944
	ds_write_b16_d16_hi v0, v248 offset:11216
	ds_write_b16 v0, v249 offset:11488
	ds_write_b16_d16_hi v0, v249 offset:11760
	ds_write_b16 v0, v250 offset:13120
	ds_write_b16_d16_hi v0, v250 offset:13392
	ds_write_b16 v0, v251 offset:13664
	ds_write_b16_d16_hi v0, v251 offset:13936
	ds_write_b16 v0, v252 offset:15296
	ds_write_b16_d16_hi v0, v252 offset:15568
	ds_write_b16 v0, v253 offset:15840
	ds_write_b16_d16_hi v0, v253 offset:16112
	s_waitcnt lgkmcnt(0)
	s_barrier
	ds_read_b128 v[8:11], v1
	ds_read_b128 v[12:15], v1 offset:4352
	ds_read_b128 v[16:19], v1 offset:8704
	ds_read_b128 v[20:23], v1 offset:13056
	ds_read_b128 v[24:27], v1 offset:17408
	ds_read_b128 v[28:31], v1 offset:21760
	ds_read_b128 v[32:35], v1 offset:26112
	ds_read_b128 v[36:39], v1 offset:30464
	s_and_b64 exec, exec, s[42:43]
	s_add_u32 s40, s46, 0x49000
	s_addc_u32 s41, s47, 0
	s_waitcnt lgkmcnt(7)
	global_store_dwordx4 v2, v[8:11], s[40:41]
	s_add_u32 s40, s46, 0x5b400
	s_addc_u32 s41, s47, 0
	s_waitcnt lgkmcnt(6)
	global_store_dwordx4 v2, v[12:15], s[40:41]
	s_add_u32 s40, s46, 0x6d800
	s_addc_u32 s41, s47, 0
	s_waitcnt lgkmcnt(5)
	global_store_dwordx4 v2, v[16:19], s[40:41]
	s_add_u32 s40, s46, 0x7fc00
	s_addc_u32 s41, s47, 0
	s_waitcnt lgkmcnt(4)
	global_store_dwordx4 v2, v[20:23], s[40:41]
	s_add_u32 s40, s46, 0xdb000
	s_addc_u32 s41, s47, 0
	s_waitcnt lgkmcnt(3)
	global_store_dwordx4 v2, v[24:27], s[40:41]
	s_add_u32 s40, s46, 0xed400
	s_addc_u32 s41, s47, 0
	s_waitcnt lgkmcnt(2)
	global_store_dwordx4 v2, v[28:31], s[40:41]
	s_add_u32 s40, s46, 0xff800
	s_addc_u32 s41, s47, 0
	s_waitcnt lgkmcnt(1)
	global_store_dwordx4 v2, v[32:35], s[40:41]
	s_add_u32 s40, s46, 0x111c00
	s_addc_u32 s41, s47, 0
	s_waitcnt lgkmcnt(0)
	global_store_dwordx4 v2, v[36:39], s[40:41]
	s_mov_b64 exec, -1
	v_mov_b32_e32 v0, 0
	v_mov_b32_e32 v1, 0
	v_mov_b32_e32 v2, 0
	v_mov_b32_e32 v3, 0
	v_mov_b32_e32 v4, 0
	v_mov_b32_e32 v5, 0
	v_mov_b32_e32 v6, 0
	v_mov_b32_e32 v7, 0
	v_mov_b32_e32 v8, 0
	v_mov_b32_e32 v9, 0
	v_mov_b32_e32 v10, 0
	v_mov_b32_e32 v11, 0
	v_mov_b32_e32 v12, 0
	v_mov_b32_e32 v13, 0
	v_mov_b32_e32 v14, 0
	v_mov_b32_e32 v15, 0
	v_mov_b32_e32 v16, 0
	v_mov_b32_e32 v17, 0
	v_mov_b32_e32 v18, 0
	v_mov_b32_e32 v19, 0
	v_mov_b32_e32 v20, 0
	v_mov_b32_e32 v21, 0
	v_mov_b32_e32 v22, 0
	v_mov_b32_e32 v23, 0
	v_mov_b32_e32 v24, 0
	v_mov_b32_e32 v25, 0
	v_mov_b32_e32 v26, 0
	v_mov_b32_e32 v27, 0
	v_mov_b32_e32 v28, 0
	v_mov_b32_e32 v29, 0
	v_mov_b32_e32 v30, 0
	v_mov_b32_e32 v31, 0
	v_mov_b32_e32 v32, 0
	v_mov_b32_e32 v33, 0
	v_mov_b32_e32 v34, 0
	v_mov_b32_e32 v35, 0
	v_mov_b32_e32 v36, 0
	v_mov_b32_e32 v37, 0
	v_mov_b32_e32 v38, 0
	v_mov_b32_e32 v39, 0
.Lv5_a_0:
	v_readfirstlane_b32 s40, v180
	v_readfirstlane_b32 s41, v181
	v_readfirstlane_b32 s42, v178
	v_readfirstlane_b32 s43, v179
	v_lshrrev_b32_e32 v198, 3, v182
	v_and_b32_e32 v199, 7, v182
	v_lshlrev_b32_e32 v198, 11, v198
	v_lshl_or_b32 v190, v199, 4, v198
	s_lshl_b32 s44, s33, 8
	s_sub_u32 s40, s40, s44
	s_subb_u32 s41, s41, 0
	s_sub_u32 s42, s42, s44
	s_subb_u32 s43, s43, 0
	s_add_u32 s40, s40, 0x2957980
	s_addc_u32 s41, s41, 0
	s_add_u32 s42, s42, 0x80
	s_addc_u32 s43, s43, 0
	v_add_u32_e32 v191, 0x10000, v190
	v_add_u32_e32 v192, 0x20000, v190
	v_add_u32_e32 v193, 0x30000, v190
	v_add_u32_e32 v194, 0x40000, v190
	v_add_u32_e32 v195, 0x50000, v190
	v_add_u32_e32 v196, 0x60000, v190
	v_add_u32_e32 v197, 0x70000, v190
	s_waitcnt lgkmcnt(0)
	s_barrier
	s_cmp_eq_u32 s45, 0
	s_cbranch_scc1 .Lv5_b_0
	s_waitcnt vmcnt(16)
	s_mov_b32 s45, 0
	s_branch .Lv5_c_0

.Lv5_c_0:
	ds_write_b128 v189, v[164:167]
	ds_write_b128 v189, v[128:131] offset:4608
	ds_write_b128 v189, v[132:135] offset:9216
	ds_write_b128 v189, v[136:139] offset:13824
	ds_write_b128 v189, v[144:147] offset:18432
	ds_write_b128 v189, v[148:151] offset:23040
	ds_write_b128 v189, v[152:155] offset:27648
	ds_write_b128 v189, v[156:159] offset:32256
	ds_write_b128 v189, v[140:143] offset:36864
	ds_write_b128 v189, v[160:163] offset:41472
	ds_write_b128 v189, v[168:171] offset:46080
	ds_write_b128 v189, v[172:175] offset:50688
	global_load_dwordx4 v[164:167], v190, s[40:41]
	global_load_dwordx4 v[128:131], v191, s[40:41]
	global_load_dwordx4 v[132:135], v192, s[40:41]
	global_load_dwordx4 v[136:139], v193, s[40:41]
	global_load_dwordx4 v[144:147], v194, s[40:41]
	global_load_dwordx4 v[148:151], v195, s[40:41]
	s_waitcnt lgkmcnt(0)
	s_barrier
.LBB0_302:
	ds_read_b128 v[216:219], v176 offset:36864
	ds_read_b128 v[200:203], v188
	ds_read_b128 v[220:223], v176 offset:41472
	ds_read_b128 v[204:207], v188 offset:4608
	ds_read_b128 v[208:211], v188 offset:9216
	ds_read_b128 v[212:215], v187
	s_waitcnt lgkmcnt(4)
	v_mfma_f32_32x32x16_bf16 v[112:127], v[200:203], v[216:219], v[112:127]
	ds_read_b128 v[240:243], v176 offset:36896
	global_load_dwordx4 v[140:143], v190, s[42:43]
	s_waitcnt lgkmcnt(4)
	v_mfma_f32_32x32x16_bf16 v[96:111], v[200:203], v[220:223], v[96:111]
	ds_read_b128 v[224:227], v188 offset:32
	global_load_dwordx4 v[160:163], v191, s[42:43]
	s_waitcnt lgkmcnt(4)
	v_mfma_f32_32x32x16_bf16 v[80:95], v[204:207], v[216:219], v[80:95]
	ds_read_b128 v[244:247], v176 offset:41504
	global_load_dwordx4 v[168:171], v192, s[42:43]
	s_waitcnt lgkmcnt(5)
	v_mfma_f32_32x32x16_bf16 v[64:79], v[204:207], v[220:223], v[64:79]
	ds_read_b128 v[228:231], v188 offset:4640
	global_load_dwordx4 v[172:175], v193, s[42:43]
	s_waitcnt lgkmcnt(5)
	v_mfma_f32_32x32x16_bf16 v[48:63], v[208:211], v[216:219], v[48:63]
	ds_read_b128 v[232:235], v188 offset:9248
	global_load_dwordx4 v[152:155], v196, s[40:41]
	s_waitcnt lgkmcnt(6)
	v_mfma_f32_32x32x16_bf16 v[32:47], v[208:211], v[220:223], v[32:47]
	ds_read_b128 v[236:239], v187 offset:32
	global_load_dwordx4 v[156:159], v197, s[40:41]
	s_add_u32 s40, s40, 0x80
	s_addc_u32 s41, s41, 0
	s_add_u32 s42, s42, 0x80
	s_addc_u32 s43, s43, 0
	s_add_u32 s16, s16, 0x80
	s_waitcnt lgkmcnt(6)
	v_mfma_f32_32x32x16_bf16 v[16:31], v[212:215], v[216:219], v[16:31]
	s_waitcnt lgkmcnt(6)
	v_mfma_f32_32x32x16_bf16 v[0:15], v[212:215], v[220:223], v[0:15]
	s_waitcnt lgkmcnt(4)
	v_mfma_f32_32x32x16_bf16 v[112:127], v[224:227], v[240:243], v[112:127]
	ds_read_b128 v[200:203], v188 offset:64
	s_waitcnt lgkmcnt(4)
	v_mfma_f32_32x32x16_bf16 v[96:111], v[224:227], v[244:247], v[96:111]
	ds_read_b128 v[204:207], v188 offset:4672
	s_waitcnt lgkmcnt(4)
	v_mfma_f32_32x32x16_bf16 v[80:95], v[228:231], v[240:243], v[80:95]
	ds_read_b128 v[208:211], v188 offset:9280
	s_waitcnt lgkmcnt(5)
	v_mfma_f32_32x32x16_bf16 v[64:79], v[228:231], v[244:247], v[64:79]
	ds_read_b128 v[212:215], v187 offset:64
	s_waitcnt lgkmcnt(5)
	v_mfma_f32_32x32x16_bf16 v[48:63], v[232:235], v[240:243], v[48:63]
	ds_read_b128 v[216:219], v176 offset:36928
	s_waitcnt lgkmcnt(6)
	v_mfma_f32_32x32x16_bf16 v[32:47], v[232:235], v[244:247], v[32:47]
	ds_read_b128 v[220:223], v176 offset:41536
	s_waitcnt lgkmcnt(6)
	v_mfma_f32_32x32x16_bf16 v[16:31], v[236:239], v[240:243], v[16:31]
	s_waitcnt lgkmcnt(6)
	v_mfma_f32_32x32x16_bf16 v[0:15], v[236:239], v[244:247], v[0:15]
	s_waitcnt lgkmcnt(1)
	v_mfma_f32_32x32x16_bf16 v[112:127], v[200:203], v[216:219], v[112:127]
	ds_read_b128 v[224:227], v188 offset:96
	s_waitcnt lgkmcnt(1)
	v_mfma_f32_32x32x16_bf16 v[96:111], v[200:203], v[220:223], v[96:111]
	ds_read_b128 v[228:231], v188 offset:4704
	s_waitcnt lgkmcnt(3)
	v_mfma_f32_32x32x16_bf16 v[80:95], v[204:207], v[216:219], v[80:95]
	ds_read_b128 v[232:235], v188 offset:9312
	s_waitcnt lgkmcnt(3)
	v_mfma_f32_32x32x16_bf16 v[64:79], v[204:207], v[220:223], v[64:79]
	ds_read_b128 v[236:239], v187 offset:96
	s_waitcnt lgkmcnt(5)
	v_mfma_f32_32x32x16_bf16 v[48:63], v[208:211], v[216:219], v[48:63]
	ds_read_b128 v[240:243], v176 offset:36960
	s_waitcnt lgkmcnt(5)
	v_mfma_f32_32x32x16_bf16 v[32:47], v[208:211], v[220:223], v[32:47]
	ds_read_b128 v[244:247], v176 offset:41568
	s_waitcnt lgkmcnt(7)
	v_mfma_f32_32x32x16_bf16 v[16:31], v[212:215], v[216:219], v[16:31]
	s_waitcnt lgkmcnt(6)
	v_mfma_f32_32x32x16_bf16 v[0:15], v[212:215], v[220:223], v[0:15]
	s_waitcnt lgkmcnt(0)
	s_barrier
	s_waitcnt vmcnt(6)
	s_waitcnt lgkmcnt(1)
	v_mfma_f32_32x32x16_bf16 v[112:127], v[224:227], v[240:243], v[112:127]
	ds_write_b128 v189, v[164:167]
	ds_write_b128 v189, v[128:131] offset:4608
	s_waitcnt lgkmcnt(2)
	v_mfma_f32_32x32x16_bf16 v[96:111], v[224:227], v[244:247], v[96:111]
	ds_write_b128 v189, v[132:135] offset:9216
	global_load_dwordx4 v[164:167], v190, s[40:41]
	s_waitcnt lgkmcnt(4)
	v_mfma_f32_32x32x16_bf16 v[80:95], v[228:231], v[240:243], v[80:95]
	ds_write_b128 v189, v[136:139] offset:13824
	ds_write_b128 v189, v[144:147] offset:18432
	global_load_dwordx4 v[128:131], v191, s[40:41]
	s_waitcnt lgkmcnt(5)
	v_mfma_f32_32x32x16_bf16 v[64:79], v[228:231], v[244:247], v[64:79]
	ds_write_b128 v189, v[148:151] offset:23040
	global_load_dwordx4 v[132:135], v192, s[40:41]
	s_waitcnt lgkmcnt(7)
	v_mfma_f32_32x32x16_bf16 v[48:63], v[232:235], v[240:243], v[48:63]
	s_waitcnt vmcnt(8)
	ds_write_b128 v189, v[140:143] offset:36864
	s_waitcnt vmcnt(7)
	ds_write_b128 v189, v[160:163] offset:41472
	global_load_dwordx4 v[136:139], v193, s[40:41]
	s_waitcnt lgkmcnt(8)
	v_mfma_f32_32x32x16_bf16 v[32:47], v[232:235], v[244:247], v[32:47]
	s_waitcnt vmcnt(7)
	ds_write_b128 v189, v[168:171] offset:46080
	global_load_dwordx4 v[144:147], v194, s[40:41]
	s_waitcnt lgkmcnt(10)
	v_mfma_f32_32x32x16_bf16 v[16:31], v[236:239], v[240:243], v[16:31]
	s_waitcnt vmcnt(7)
	ds_write_b128 v189, v[172:175] offset:50688
	s_waitcnt vmcnt(6)
	ds_write_b128 v189, v[152:155] offset:27648
	global_load_dwordx4 v[148:151], v195, s[40:41]
	s_waitcnt lgkmcnt(11)
	v_mfma_f32_32x32x16_bf16 v[0:15], v[236:239], v[244:247], v[0:15]
	s_waitcnt vmcnt(6)
	ds_write_b128 v189, v[156:159] offset:32256
	s_waitcnt lgkmcnt(0)
	s_barrier
	s_cmpk_lg_i32 s16, 0x780
	s_cbranch_scc1 .LBB0_302
	ds_read_b128 v[216:219], v176 offset:36864
	ds_read_b128 v[200:203], v188
	ds_read_b128 v[220:223], v176 offset:41472
	ds_read_b128 v[204:207], v188 offset:4608
	ds_read_b128 v[208:211], v188 offset:9216
	ds_read_b128 v[212:215], v187
	s_waitcnt lgkmcnt(4)
	v_mfma_f32_32x32x16_bf16 v[112:127], v[200:203], v[216:219], v[112:127]
	ds_read_b128 v[240:243], v176 offset:36896
	s_waitcnt lgkmcnt(4)
	v_mfma_f32_32x32x16_bf16 v[96:111], v[200:203], v[220:223], v[96:111]
	ds_read_b128 v[224:227], v188 offset:32
	s_waitcnt lgkmcnt(4)
	v_mfma_f32_32x32x16_bf16 v[80:95], v[204:207], v[216:219], v[80:95]
	ds_read_b128 v[244:247], v176 offset:41504
	s_waitcnt lgkmcnt(5)
	v_mfma_f32_32x32x16_bf16 v[64:79], v[204:207], v[220:223], v[64:79]
	ds_read_b128 v[228:231], v188 offset:4640
	s_waitcnt lgkmcnt(5)
	v_mfma_f32_32x32x16_bf16 v[48:63], v[208:211], v[216:219], v[48:63]
	ds_read_b128 v[232:235], v188 offset:9248
	s_waitcnt lgkmcnt(6)
	v_mfma_f32_32x32x16_bf16 v[32:47], v[208:211], v[220:223], v[32:47]
	ds_read_b128 v[236:239], v187 offset:32
	s_waitcnt lgkmcnt(6)
	v_mfma_f32_32x32x16_bf16 v[16:31], v[212:215], v[216:219], v[16:31]
	s_waitcnt lgkmcnt(6)
	v_mfma_f32_32x32x16_bf16 v[0:15], v[212:215], v[220:223], v[0:15]
	s_waitcnt lgkmcnt(4)
	v_mfma_f32_32x32x16_bf16 v[112:127], v[224:227], v[240:243], v[112:127]
	ds_read_b128 v[200:203], v188 offset:64
	s_waitcnt lgkmcnt(4)
	v_mfma_f32_32x32x16_bf16 v[96:111], v[224:227], v[244:247], v[96:111]
	ds_read_b128 v[204:207], v188 offset:4672
	s_waitcnt lgkmcnt(4)
	v_mfma_f32_32x32x16_bf16 v[80:95], v[228:231], v[240:243], v[80:95]
	ds_read_b128 v[208:211], v188 offset:9280
	s_waitcnt lgkmcnt(5)
	v_mfma_f32_32x32x16_bf16 v[64:79], v[228:231], v[244:247], v[64:79]
	ds_read_b128 v[212:215], v187 offset:64
	s_waitcnt lgkmcnt(5)
	v_mfma_f32_32x32x16_bf16 v[48:63], v[232:235], v[240:243], v[48:63]
	ds_read_b128 v[216:219], v176 offset:36928
	s_waitcnt lgkmcnt(6)
	v_mfma_f32_32x32x16_bf16 v[32:47], v[232:235], v[244:247], v[32:47]
	ds_read_b128 v[220:223], v176 offset:41536
	s_waitcnt lgkmcnt(6)
	v_mfma_f32_32x32x16_bf16 v[16:31], v[236:239], v[240:243], v[16:31]
	s_waitcnt lgkmcnt(6)
	v_mfma_f32_32x32x16_bf16 v[0:15], v[236:239], v[244:247], v[0:15]
	s_waitcnt lgkmcnt(1)
	v_mfma_f32_32x32x16_bf16 v[112:127], v[200:203], v[216:219], v[112:127]
	ds_read_b128 v[224:227], v188 offset:96
	s_waitcnt lgkmcnt(1)
	v_mfma_f32_32x32x16_bf16 v[96:111], v[200:203], v[220:223], v[96:111]
	ds_read_b128 v[228:231], v188 offset:4704
	s_waitcnt lgkmcnt(3)
	v_mfma_f32_32x32x16_bf16 v[80:95], v[204:207], v[216:219], v[80:95]
	ds_read_b128 v[232:235], v188 offset:9312
	s_waitcnt lgkmcnt(3)
	v_mfma_f32_32x32x16_bf16 v[64:79], v[204:207], v[220:223], v[64:79]
	ds_read_b128 v[236:239], v187 offset:96
	s_waitcnt lgkmcnt(5)
	v_mfma_f32_32x32x16_bf16 v[48:63], v[208:211], v[216:219], v[48:63]
	ds_read_b128 v[240:243], v176 offset:36960
	s_waitcnt lgkmcnt(5)
	v_mfma_f32_32x32x16_bf16 v[32:47], v[208:211], v[220:223], v[32:47]
	ds_read_b128 v[244:247], v176 offset:41568
	s_waitcnt lgkmcnt(7)
	v_mfma_f32_32x32x16_bf16 v[16:31], v[212:215], v[216:219], v[16:31]
	s_waitcnt lgkmcnt(6)
	v_mfma_f32_32x32x16_bf16 v[0:15], v[212:215], v[220:223], v[0:15]
	s_waitcnt lgkmcnt(1)
	v_mfma_f32_32x32x16_bf16 v[112:127], v[224:227], v[240:243], v[112:127]
	s_waitcnt lgkmcnt(0)
	v_mfma_f32_32x32x16_bf16 v[96:111], v[224:227], v[244:247], v[96:111]
	s_waitcnt lgkmcnt(1)
	v_mfma_f32_32x32x16_bf16 v[80:95], v[228:231], v[240:243], v[80:95]
	s_waitcnt lgkmcnt(0)
	v_mfma_f32_32x32x16_bf16 v[64:79], v[228:231], v[244:247], v[64:79]
	s_waitcnt lgkmcnt(1)
	v_mfma_f32_32x32x16_bf16 v[48:63], v[232:235], v[240:243], v[48:63]
	s_waitcnt lgkmcnt(0)
	v_mfma_f32_32x32x16_bf16 v[32:47], v[232:235], v[244:247], v[32:47]
	s_waitcnt lgkmcnt(1)
	v_mfma_f32_32x32x16_bf16 v[16:31], v[236:239], v[240:243], v[16:31]
	s_waitcnt lgkmcnt(0)
	v_mfma_f32_32x32x16_bf16 v[0:15], v[236:239], v[244:247], v[0:15]
	s_waitcnt vmcnt(0)
	s_mul_i32 s44, s12, 0x1240
	s_add_u32 s46, s30, s44
	s_addc_u32 s47, s31, 0
	s_lshl_b32 s44, s8, 1
	s_add_u32 s46, s46, s44
	s_addc_u32 s47, s47, 0
	s_add_u32 s46, s46, 0x7157900
	s_addc_u32 s47, s47, 0
	s_cmp_eq_u32 s8, 0x900
	s_cselect_b32 s45, 2, 1
	v_cvt_pk_bf16_f32 v190, v112, v113
	v_cvt_pk_bf16_f32 v191, v114, v115
	v_cvt_pk_bf16_f32 v192, v116, v117
	v_cvt_pk_bf16_f32 v193, v118, v119
	v_cvt_pk_bf16_f32 v194, v120, v121
	v_cvt_pk_bf16_f32 v195, v122, v123
	v_cvt_pk_bf16_f32 v196, v124, v125
	v_cvt_pk_bf16_f32 v197, v126, v127
	v_cvt_pk_bf16_f32 v198, v96, v97
	v_cvt_pk_bf16_f32 v199, v98, v99
	v_cvt_pk_bf16_f32 v200, v100, v101
	v_cvt_pk_bf16_f32 v201, v102, v103
	v_cvt_pk_bf16_f32 v202, v104, v105
	v_cvt_pk_bf16_f32 v203, v106, v107
	v_cvt_pk_bf16_f32 v204, v108, v109
	v_cvt_pk_bf16_f32 v205, v110, v111
	v_cvt_pk_bf16_f32 v206, v80, v81
	v_cvt_pk_bf16_f32 v207, v82, v83
	v_cvt_pk_bf16_f32 v208, v84, v85
	v_cvt_pk_bf16_f32 v209, v86, v87
	v_cvt_pk_bf16_f32 v210, v88, v89
	v_cvt_pk_bf16_f32 v211, v90, v91
	v_cvt_pk_bf16_f32 v212, v92, v93
	v_cvt_pk_bf16_f32 v213, v94, v95
	v_cvt_pk_bf16_f32 v214, v64, v65
	v_cvt_pk_bf16_f32 v215, v66, v67
	v_cvt_pk_bf16_f32 v216, v68, v69
	v_cvt_pk_bf16_f32 v217, v70, v71
	v_cvt_pk_bf16_f32 v218, v72, v73
	v_cvt_pk_bf16_f32 v219, v74, v75
	v_cvt_pk_bf16_f32 v220, v76, v77
	v_cvt_pk_bf16_f32 v221, v78, v79
	v_cvt_pk_bf16_f32 v222, v48, v49
	v_cvt_pk_bf16_f32 v223, v50, v51
	v_cvt_pk_bf16_f32 v224, v52, v53
	v_cvt_pk_bf16_f32 v225, v54, v55
	v_cvt_pk_bf16_f32 v226, v56, v57
	v_cvt_pk_bf16_f32 v227, v58, v59
	v_cvt_pk_bf16_f32 v228, v60, v61
	v_cvt_pk_bf16_f32 v229, v62, v63
	v_cvt_pk_bf16_f32 v230, v32, v33
	v_cvt_pk_bf16_f32 v231, v34, v35
	v_cvt_pk_bf16_f32 v232, v36, v37
	v_cvt_pk_bf16_f32 v233, v38, v39
	v_cvt_pk_bf16_f32 v234, v40, v41
	v_cvt_pk_bf16_f32 v235, v42, v43
	v_cvt_pk_bf16_f32 v236, v44, v45
	v_cvt_pk_bf16_f32 v237, v46, v47
	v_cvt_pk_bf16_f32 v238, v16, v17
	v_cvt_pk_bf16_f32 v239, v18, v19
	v_cvt_pk_bf16_f32 v240, v20, v21
	v_cvt_pk_bf16_f32 v241, v22, v23
	v_cvt_pk_bf16_f32 v242, v24, v25
	v_cvt_pk_bf16_f32 v243, v26, v27
	v_cvt_pk_bf16_f32 v244, v28, v29
	v_cvt_pk_bf16_f32 v245, v30, v31
	v_cvt_pk_bf16_f32 v246, v0, v1
	v_cvt_pk_bf16_f32 v247, v2, v3
	v_cvt_pk_bf16_f32 v248, v4, v5
	v_cvt_pk_bf16_f32 v249, v6, v7
	v_cvt_pk_bf16_f32 v250, v8, v9
	v_cvt_pk_bf16_f32 v251, v10, v11
	v_cvt_pk_bf16_f32 v252, v12, v13
	v_cvt_pk_bf16_f32 v253, v14, v15
	s_branch .Lmt4_tail_0

.Lw_flush_2:
	s_cmp_eq_u32 s48, 0
	s_cbranch_scc1 .LBB0_1273
	v_and_b32_e32 v3, 15, v182
	v_cmp_gt_u32_e64 s[44:45], 4, v3
	s_cmp_eq_u32 s48, 2
	s_cselect_b64 s[44:45], s[44:45], -1
	v_lshrrev_b32_e32 v4, 4, v182
	v_mul_u32_u24_e32 v2, 0x1240, v4
	v_lshl_add_u32 v2, v3, 4, v2
	v_mul_u32_u24_e32 v1, 0x110, v4
	v_lshl_add_u32 v1, v3, 4, v1
	v_lshrrev_b32_e32 v3, 7, v182
	v_bfe_u32 v4, v182, 5, 1
	v_lshlrev_b32_e32 v3, 6, v3
	v_lshl_or_b32 v3, v4, 2, v3
	v_mul_u32_u24_e32 v3, 136, v3
	v_and_b32_e32 v4, 0x5f, v182
	v_add_lshl_u32 v0, v3, v4, 1
	s_barrier
	ds_write_b16 v0, v190
	ds_write_b16_d16_hi v0, v190 offset:272
	ds_write_b16 v0, v191 offset:544
	ds_write_b16_d16_hi v0, v191 offset:816
	ds_write_b16 v0, v192 offset:2176
	ds_write_b16_d16_hi v0, v192 offset:2448
	ds_write_b16 v0, v193 offset:2720
	ds_write_b16_d16_hi v0, v193 offset:2992
	ds_write_b16 v0, v194 offset:4352
	ds_write_b16_d16_hi v0, v194 offset:4624
	ds_write_b16 v0, v195 offset:4896
	ds_write_b16_d16_hi v0, v195 offset:5168
	ds_write_b16 v0, v196 offset:6528
	ds_write_b16_d16_hi v0, v196 offset:6800
	ds_write_b16 v0, v197 offset:7072
	ds_write_b16_d16_hi v0, v197 offset:7344
	ds_write_b16 v0, v198 offset:64
	ds_write_b16_d16_hi v0, v198 offset:336
	ds_write_b16 v0, v199 offset:608
	ds_write_b16_d16_hi v0, v199 offset:880
	ds_write_b16 v0, v200 offset:2240
	ds_write_b16_d16_hi v0, v200 offset:2512
	ds_write_b16 v0, v201 offset:2784
	ds_write_b16_d16_hi v0, v201 offset:3056
	ds_write_b16 v0, v202 offset:4416
	ds_write_b16_d16_hi v0, v202 offset:4688
	ds_write_b16 v0, v203 offset:4960
	ds_write_b16_d16_hi v0, v203 offset:5232
	ds_write_b16 v0, v204 offset:6592
	ds_write_b16_d16_hi v0, v204 offset:6864
	ds_write_b16 v0, v205 offset:7136
	ds_write_b16_d16_hi v0, v205 offset:7408
	ds_write_b16 v0, v206 offset:8704
	ds_write_b16_d16_hi v0, v206 offset:8976
	ds_write_b16 v0, v207 offset:9248
	ds_write_b16_d16_hi v0, v207 offset:9520
	ds_write_b16 v0, v208 offset:10880
	ds_write_b16_d16_hi v0, v208 offset:11152
	ds_write_b16 v0, v209 offset:11424
	ds_write_b16_d16_hi v0, v209 offset:11696
	ds_write_b16 v0, v210 offset:13056
	ds_write_b16_d16_hi v0, v210 offset:13328
	ds_write_b16 v0, v211 offset:13600
	ds_write_b16_d16_hi v0, v211 offset:13872
	ds_write_b16 v0, v212 offset:15232
	ds_write_b16_d16_hi v0, v212 offset:15504
	ds_write_b16 v0, v213 offset:15776
	ds_write_b16_d16_hi v0, v213 offset:16048
	ds_write_b16 v0, v214 offset:8768
	ds_write_b16_d16_hi v0, v214 offset:9040
	ds_write_b16 v0, v215 offset:9312
	ds_write_b16_d16_hi v0, v215 offset:9584
	ds_write_b16 v0, v216 offset:10944
	ds_write_b16_d16_hi v0, v216 offset:11216
	ds_write_b16 v0, v217 offset:11488
	ds_write_b16_d16_hi v0, v217 offset:11760
	ds_write_b16 v0, v218 offset:13120
	ds_write_b16_d16_hi v0, v218 offset:13392
	ds_write_b16 v0, v219 offset:13664
	ds_write_b16_d16_hi v0, v219 offset:13936
	ds_write_b16 v0, v220 offset:15296
	ds_write_b16_d16_hi v0, v220 offset:15568
	ds_write_b16 v0, v221 offset:15840
	ds_write_b16_d16_hi v0, v221 offset:16112
	s_waitcnt lgkmcnt(0)
	s_barrier
	ds_read_b128 v[8:11], v1
	ds_read_b128 v[12:15], v1 offset:4352
	ds_read_b128 v[16:19], v1 offset:8704
	ds_read_b128 v[20:23], v1 offset:13056
	ds_read_b128 v[24:27], v1 offset:17408
	ds_read_b128 v[28:31], v1 offset:21760
	ds_read_b128 v[32:35], v1 offset:26112
	ds_read_b128 v[36:39], v1 offset:30464
	s_and_b64 exec, exec, s[44:45]
	s_add_u32 s42, s46, 0x0
	s_addc_u32 s43, s47, 0
	s_waitcnt lgkmcnt(7)
	global_store_dwordx4 v2, v[8:11], s[42:43]
	s_add_u32 s42, s46, 0x12400
	s_addc_u32 s43, s47, 0
	s_waitcnt lgkmcnt(6)
	global_store_dwordx4 v2, v[12:15], s[42:43]
	s_add_u32 s42, s46, 0x24800
	s_addc_u32 s43, s47, 0
	s_waitcnt lgkmcnt(5)
	global_store_dwordx4 v2, v[16:19], s[42:43]
	s_add_u32 s42, s46, 0x36c00
	s_addc_u32 s43, s47, 0
	s_waitcnt lgkmcnt(4)
	global_store_dwordx4 v2, v[20:23], s[42:43]
	s_add_u32 s42, s46, 0x92000
	s_addc_u32 s43, s47, 0
	s_waitcnt lgkmcnt(3)
	global_store_dwordx4 v2, v[24:27], s[42:43]
	s_add_u32 s42, s46, 0xa4400
	s_addc_u32 s43, s47, 0
	s_waitcnt lgkmcnt(2)
	global_store_dwordx4 v2, v[28:31], s[42:43]
	s_add_u32 s42, s46, 0xb6800
	s_addc_u32 s43, s47, 0
	s_waitcnt lgkmcnt(1)
	global_store_dwordx4 v2, v[32:35], s[42:43]
	s_add_u32 s42, s46, 0xc8c00
	s_addc_u32 s43, s47, 0
	s_waitcnt lgkmcnt(0)
	global_store_dwordx4 v2, v[36:39], s[42:43]
	s_mov_b64 exec, -1
	s_barrier
	ds_write_b16 v0, v222
	ds_write_b16_d16_hi v0, v222 offset:272
	ds_write_b16 v0, v223 offset:544
	ds_write_b16_d16_hi v0, v223 offset:816
	ds_write_b16 v0, v224 offset:2176
	ds_write_b16_d16_hi v0, v224 offset:2448
	ds_write_b16 v0, v225 offset:2720
	ds_write_b16_d16_hi v0, v225 offset:2992
	ds_write_b16 v0, v226 offset:4352
	ds_write_b16_d16_hi v0, v226 offset:4624
	ds_write_b16 v0, v227 offset:4896
	ds_write_b16_d16_hi v0, v227 offset:5168
	ds_write_b16 v0, v228 offset:6528
	ds_write_b16_d16_hi v0, v228 offset:6800
	ds_write_b16 v0, v229 offset:7072
	ds_write_b16_d16_hi v0, v229 offset:7344
	ds_write_b16 v0, v230 offset:64
	ds_write_b16_d16_hi v0, v230 offset:336
	ds_write_b16 v0, v231 offset:608
	ds_write_b16_d16_hi v0, v231 offset:880
	ds_write_b16 v0, v232 offset:2240
	ds_write_b16_d16_hi v0, v232 offset:2512
	ds_write_b16 v0, v233 offset:2784
	ds_write_b16_d16_hi v0, v233 offset:3056
	ds_write_b16 v0, v234 offset:4416
	ds_write_b16_d16_hi v0, v234 offset:4688
	ds_write_b16 v0, v235 offset:4960
	ds_write_b16_d16_hi v0, v235 offset:5232
	ds_write_b16 v0, v236 offset:6592
	ds_write_b16_d16_hi v0, v236 offset:6864
	ds_write_b16 v0, v237 offset:7136
	ds_write_b16_d16_hi v0, v237 offset:7408
	ds_write_b16 v0, v238 offset:8704
	ds_write_b16_d16_hi v0, v238 offset:8976
	ds_write_b16 v0, v239 offset:9248
	ds_write_b16_d16_hi v0, v239 offset:9520
	ds_write_b16 v0, v240 offset:10880
	ds_write_b16_d16_hi v0, v240 offset:11152
	ds_write_b16 v0, v241 offset:11424
	ds_write_b16_d16_hi v0, v241 offset:11696
	ds_write_b16 v0, v242 offset:13056
	ds_write_b16_d16_hi v0, v242 offset:13328
	ds_write_b16 v0, v243 offset:13600
	ds_write_b16_d16_hi v0, v243 offset:13872
	ds_write_b16 v0, v244 offset:15232
	ds_write_b16_d16_hi v0, v244 offset:15504
	ds_write_b16 v0, v245 offset:15776
	ds_write_b16_d16_hi v0, v245 offset:16048
	ds_write_b16 v0, v246 offset:8768
	ds_write_b16_d16_hi v0, v246 offset:9040
	ds_write_b16 v0, v247 offset:9312
	ds_write_b16_d16_hi v0, v247 offset:9584
	ds_write_b16 v0, v248 offset:10944
	ds_write_b16_d16_hi v0, v248 offset:11216
	ds_write_b16 v0, v249 offset:11488
	ds_write_b16_d16_hi v0, v249 offset:11760
	ds_write_b16 v0, v250 offset:13120
	ds_write_b16_d16_hi v0, v250 offset:13392
	ds_write_b16 v0, v251 offset:13664
	ds_write_b16_d16_hi v0, v251 offset:13936
	ds_write_b16 v0, v252 offset:15296
	ds_write_b16_d16_hi v0, v252 offset:15568
	ds_write_b16 v0, v253 offset:15840
	ds_write_b16_d16_hi v0, v253 offset:16112
	s_waitcnt lgkmcnt(0)
	s_barrier
	ds_read_b128 v[8:11], v1
	ds_read_b128 v[12:15], v1 offset:4352
	ds_read_b128 v[16:19], v1 offset:8704
	ds_read_b128 v[20:23], v1 offset:13056
	ds_read_b128 v[24:27], v1 offset:17408
	ds_read_b128 v[28:31], v1 offset:21760
	ds_read_b128 v[32:35], v1 offset:26112
	ds_read_b128 v[36:39], v1 offset:30464
	s_and_b64 exec, exec, s[44:45]
	s_add_u32 s42, s46, 0x49000
	s_addc_u32 s43, s47, 0
	s_waitcnt lgkmcnt(7)
	global_store_dwordx4 v2, v[8:11], s[42:43]
	s_add_u32 s42, s46, 0x5b400
	s_addc_u32 s43, s47, 0
	s_waitcnt lgkmcnt(6)
	global_store_dwordx4 v2, v[12:15], s[42:43]
	s_add_u32 s42, s46, 0x6d800
	s_addc_u32 s43, s47, 0
	s_waitcnt lgkmcnt(5)
	global_store_dwordx4 v2, v[16:19], s[42:43]
	s_add_u32 s42, s46, 0x7fc00
	s_addc_u32 s43, s47, 0
	s_waitcnt lgkmcnt(4)
	global_store_dwordx4 v2, v[20:23], s[42:43]
	s_add_u32 s42, s46, 0xdb000
	s_addc_u32 s43, s47, 0
	s_waitcnt lgkmcnt(3)
	global_store_dwordx4 v2, v[24:27], s[42:43]
	s_add_u32 s42, s46, 0xed400
	s_addc_u32 s43, s47, 0
	s_waitcnt lgkmcnt(2)
	global_store_dwordx4 v2, v[28:31], s[42:43]
	s_add_u32 s42, s46, 0xff800
	s_addc_u32 s43, s47, 0
	s_waitcnt lgkmcnt(1)
	global_store_dwordx4 v2, v[32:35], s[42:43]
	s_add_u32 s42, s46, 0x111c00
	s_addc_u32 s43, s47, 0
	s_waitcnt lgkmcnt(0)
	global_store_dwordx4 v2, v[36:39], s[42:43]
	s_mov_b64 exec, -1
	s_mov_b32 s48, 0

.LBB0_1278:
	s_and_b64 vcc, exec, s[4:5]
	s_cbranch_vccnz .LBB0_1273
	s_mov_b32 s56, s18
	s_mov_b32 s48, 0
	s_branch .LBB0_1282

.LBB0_1282:
	s_mul_hi_u32 s0, s56, s25
	s_mul_i32 s1, s0, s20
	s_sub_i32 s1, s56, s1
	s_add_i32 s8, s0, 1
	s_sub_i32 s12, s1, s20
	s_cmp_ge_u32 s1, s20
	s_cselect_b32 s0, s8, s0
	s_cselect_b32 s1, s12, s1
	s_add_i32 s8, s0, 1
	s_cmp_ge_u32 s1, s20
	s_cselect_b32 s1, s8, s0
	s_add_i32 s0, s1, s23
	s_mul_i32 s1, s1, s20
	s_sub_i32 s1, s56, s1
	s_add_i32 s1, s1, s19
	s_mul_i32 s8, s0, 0xe38e3900
	v_alignbit_b32 v0, s8, s8, 8
	s_cmp_lt_u32 s1, 8
	v_cmp_gt_u32_e32 vcc, s26, v0
	s_cselect_b64 s[12:13], -1, 0
	s_and_b64 s[12:13], vcc, s[12:13]
	s_and_b64 vcc, exec, s[12:13]
	s_cbranch_vccnz .LBB0_1281
	s_lshl_b32 s12, s0, 8
	s_lshl_b32 s8, s1, 7
	s_mov_b64 s[0:1], s[30:31]
	v_mov_b32_e32 v0, v177
	s_mov_b32 s13, s9
	v_mbcnt_lo_u32_b32 v0, -1, v0
	v_mbcnt_hi_u32_b32 v0, -1, v0
	v_add_u32_e32 v182, s33, v0
	s_lshl_b64 s[16:17], s[12:13], 11
	v_ashrrev_i32_e32 v0, 3, v182
	v_lshlrev_b32_e32 v1, 3, v182
	s_add_u32 s58, s14, s16
	v_and_b32_e32 v6, 56, v1
	v_lshlrev_b32_e32 v1, 11, v0
	s_addc_u32 s59, s15, s17
	v_lshl_or_b32 v176, v6, 1, v1
	v_mul_lo_u32 v7, v0, s21
	v_lshl_add_u64 v[0:1], s[58:59], 0, v[176:177]
	v_add_co_u32_e32 v2, vcc, s27, v0
	s_lshl_b64 s[60:61], s[8:9], 11
	s_nop 0
	v_addc_co_u32_e32 v3, vcc, 0, v1, vcc
	v_add_co_u32_e32 v4, vcc, s34, v0
	s_add_u32 s60, s30, s60
	s_nop 0
	v_addc_co_u32_e32 v5, vcc, 0, v1, vcc
	global_load_dwordx4 v[128:131], v[2:3], off
	global_load_dwordx4 v[132:135], v[4:5], off
	v_add_co_u32_e32 v2, vcc, s35, v0
	s_addc_u32 s61, s31, s61
	s_nop 0
	v_addc_co_u32_e32 v3, vcc, 0, v1, vcc
	v_add_co_u32_e32 v4, vcc, s36, v0
	v_lshl_add_u64 v[178:179], s[60:61], 0, v[176:177]
	s_nop 0
	v_addc_co_u32_e32 v5, vcc, 0, v1, vcc
	global_load_dwordx4 v[136:139], v[2:3], off
	global_load_dwordx4 v[144:147], v[4:5], off
	v_add_co_u32_e32 v2, vcc, s37, v0
	v_bfe_u32 v185, v182, 6, 1
	s_nop 0
	v_addc_co_u32_e32 v3, vcc, 0, v1, vcc
	v_add_co_u32_e32 v4, vcc, s38, v0
	v_and_b32_e32 v184, 31, v182
	s_nop 0
	v_addc_co_u32_e32 v5, vcc, 0, v1, vcc
	v_add_co_u32_e32 v0, vcc, s39, v0
	global_load_dwordx4 v[148:151], v[2:3], off
	global_load_dwordx4 v[152:155], v[4:5], off
	v_addc_co_u32_e32 v1, vcc, 0, v1, vcc
	v_add_co_u32_e32 v2, vcc, s27, v178
	global_load_dwordx4 v[164:167], v176, s[58:59]
	global_load_dwordx4 v[140:143], v176, s[60:61]
	v_addc_co_u32_e32 v3, vcc, 0, v179, vcc
	global_load_dwordx4 v[156:159], v[0:1], off
	global_load_dwordx4 v[160:163], v[2:3], off
	v_add_co_u32_e32 v0, vcc, s34, v178
	v_bfe_u32 v186, v182, 5, 1
	s_nop 0
	v_addc_co_u32_e32 v1, vcc, 0, v179, vcc
	v_add_co_u32_e32 v2, vcc, s35, v178
	s_add_u32 s16, s30, s16
	s_nop 0
	v_addc_co_u32_e32 v3, vcc, 0, v179, vcc
	global_load_dwordx4 v[168:171], v[0:1], off
	global_load_dwordx4 v[172:175], v[2:3], off
	v_and_b32_e32 v0, 0xfffff9f, v182
	v_lshl_or_b32 v2, v185, 6, v184
	v_mul_lo_u32 v3, v0, s40
	v_or_b32_e32 v0, 0x60, v182
	v_lshlrev_b32_e32 v1, 4, v186
	v_mul_lo_u32 v4, v0, s40
	v_mul_u32_u24_e32 v2, 0x90, v2
	s_addc_u32 s17, s31, s17
	v_mov_b32_e32 v0, 0
	v_add_lshl_u32 v189, v7, v6, 1
	v_lshl_add_u64 v[180:181], s[16:17], 0, v[176:177]
	s_mov_b64 s[16:17], 0
	v_add_u32_e32 v188, v1, v3
	v_add_u32_e32 v187, v1, v4
	v_add_u32_e32 v176, v1, v2
	v_mov_b32_e32 v1, v0
	v_mov_b32_e32 v2, v0
	v_mov_b32_e32 v3, v0
	v_mov_b32_e32 v4, v0
	v_mov_b32_e32 v5, v0
	v_mov_b32_e32 v6, v0
	v_mov_b32_e32 v7, v0
	v_mov_b32_e32 v8, v0
	v_mov_b32_e32 v9, v0
	v_mov_b32_e32 v10, v0
	v_mov_b32_e32 v11, v0
	v_mov_b32_e32 v12, v0
	v_mov_b32_e32 v13, v0
	v_mov_b32_e32 v14, v0
	v_mov_b32_e32 v15, v0
	v_mov_b32_e32 v16, v0
	v_mov_b32_e32 v17, v0
	v_mov_b32_e32 v18, v0
	v_mov_b32_e32 v19, v0
	v_mov_b32_e32 v20, v0
	v_mov_b32_e32 v21, v0
	v_mov_b32_e32 v22, v0
	v_mov_b32_e32 v23, v0
	v_mov_b32_e32 v24, v0
	v_mov_b32_e32 v25, v0
	v_mov_b32_e32 v26, v0
	v_mov_b32_e32 v27, v0
	v_mov_b32_e32 v28, v0
	v_mov_b32_e32 v29, v0
	v_mov_b32_e32 v30, v0
	v_mov_b32_e32 v31, v0
	v_mov_b32_e32 v32, v0
	v_mov_b32_e32 v33, v0
	v_mov_b32_e32 v34, v0
	v_mov_b32_e32 v35, v0
	v_mov_b32_e32 v36, v0
	v_mov_b32_e32 v37, v0
	v_mov_b32_e32 v38, v0
	v_mov_b32_e32 v39, v0
	v_mov_b32_e32 v40, v0
	v_mov_b32_e32 v41, v0
	v_mov_b32_e32 v42, v0
	v_mov_b32_e32 v43, v0
	v_mov_b32_e32 v44, v0
	v_mov_b32_e32 v45, v0
	v_mov_b32_e32 v46, v0
	v_mov_b32_e32 v47, v0
	v_mov_b32_e32 v48, v0
	v_mov_b32_e32 v49, v0
	v_mov_b32_e32 v50, v0
	v_mov_b32_e32 v51, v0
	v_mov_b32_e32 v52, v0
	v_mov_b32_e32 v53, v0
	v_mov_b32_e32 v54, v0
	v_mov_b32_e32 v55, v0
	v_mov_b32_e32 v56, v0
	v_mov_b32_e32 v57, v0
	v_mov_b32_e32 v58, v0
	v_mov_b32_e32 v59, v0
	v_mov_b32_e32 v60, v0
	v_mov_b32_e32 v61, v0
	v_mov_b32_e32 v62, v0
	v_mov_b32_e32 v63, v0
	v_mov_b32_e32 v64, v0
	v_mov_b32_e32 v65, v0
	v_mov_b32_e32 v66, v0
	v_mov_b32_e32 v67, v0
	v_mov_b32_e32 v68, v0
	v_mov_b32_e32 v69, v0
	v_mov_b32_e32 v70, v0
	v_mov_b32_e32 v71, v0
	v_mov_b32_e32 v72, v0
	v_mov_b32_e32 v73, v0
	v_mov_b32_e32 v74, v0
	v_mov_b32_e32 v75, v0
	v_mov_b32_e32 v76, v0
	v_mov_b32_e32 v77, v0
	v_mov_b32_e32 v78, v0
	v_mov_b32_e32 v79, v0
	v_mov_b32_e32 v80, v0
	v_mov_b32_e32 v81, v0
	v_mov_b32_e32 v82, v0
	v_mov_b32_e32 v83, v0
	v_mov_b32_e32 v84, v0
	v_mov_b32_e32 v85, v0
	v_mov_b32_e32 v86, v0
	v_mov_b32_e32 v87, v0
	v_mov_b32_e32 v88, v0
	v_mov_b32_e32 v89, v0
	v_mov_b32_e32 v90, v0
	v_mov_b32_e32 v91, v0
	v_mov_b32_e32 v92, v0
	v_mov_b32_e32 v93, v0
	v_mov_b32_e32 v94, v0
	v_mov_b32_e32 v95, v0
	v_mov_b32_e32 v96, v0
	v_mov_b32_e32 v97, v0
	v_mov_b32_e32 v98, v0
	v_mov_b32_e32 v99, v0
	v_mov_b32_e32 v100, v0
	v_mov_b32_e32 v101, v0
	v_mov_b32_e32 v102, v0
	v_mov_b32_e32 v103, v0
	v_mov_b32_e32 v104, v0
	v_mov_b32_e32 v105, v0
	v_mov_b32_e32 v106, v0
	v_mov_b32_e32 v107, v0
	v_mov_b32_e32 v108, v0
	v_mov_b32_e32 v109, v0
	v_mov_b32_e32 v110, v0
	v_mov_b32_e32 v111, v0
	v_mov_b32_e32 v112, v0
	v_mov_b32_e32 v113, v0
	v_mov_b32_e32 v114, v0
	v_mov_b32_e32 v115, v0
	v_mov_b32_e32 v116, v0
	v_mov_b32_e32 v117, v0
	v_mov_b32_e32 v118, v0
	v_mov_b32_e32 v119, v0
	v_mov_b32_e32 v120, v0
	v_mov_b32_e32 v121, v0
	v_mov_b32_e32 v122, v0
	v_mov_b32_e32 v123, v0
	v_mov_b32_e32 v124, v0
	v_mov_b32_e32 v125, v0
	v_mov_b32_e32 v126, v0
	v_mov_b32_e32 v127, v0
	s_cmp_eq_u32 s48, 0
	s_cbranch_scc1 .Lv5_a_2
	v_and_b32_e32 v3, 15, v182
	v_cmp_gt_u32_e64 s[44:45], 4, v3
	s_cmp_eq_u32 s48, 2
	s_cselect_b64 s[44:45], s[44:45], -1
	v_lshrrev_b32_e32 v4, 4, v182
	v_mul_u32_u24_e32 v2, 0x1240, v4
	v_lshl_add_u32 v2, v3, 4, v2
	v_mul_u32_u24_e32 v1, 0x110, v4
	v_lshl_add_u32 v1, v3, 4, v1
	v_lshrrev_b32_e32 v3, 7, v182
	v_bfe_u32 v4, v182, 5, 1
	v_lshlrev_b32_e32 v3, 6, v3
	v_lshl_or_b32 v3, v4, 2, v3
	v_mul_u32_u24_e32 v3, 136, v3
	v_and_b32_e32 v4, 0x5f, v182
	v_add_lshl_u32 v0, v3, v4, 1
	s_barrier
	ds_write_b16 v0, v190
	ds_write_b16_d16_hi v0, v190 offset:272
	ds_write_b16 v0, v191 offset:544
	ds_write_b16_d16_hi v0, v191 offset:816
	ds_write_b16 v0, v192 offset:2176
	ds_write_b16_d16_hi v0, v192 offset:2448
	ds_write_b16 v0, v193 offset:2720
	ds_write_b16_d16_hi v0, v193 offset:2992
	ds_write_b16 v0, v194 offset:4352
	ds_write_b16_d16_hi v0, v194 offset:4624
	ds_write_b16 v0, v195 offset:4896
	ds_write_b16_d16_hi v0, v195 offset:5168
	ds_write_b16 v0, v196 offset:6528
	ds_write_b16_d16_hi v0, v196 offset:6800
	ds_write_b16 v0, v197 offset:7072
	ds_write_b16_d16_hi v0, v197 offset:7344
	ds_write_b16 v0, v198 offset:64
	ds_write_b16_d16_hi v0, v198 offset:336
	ds_write_b16 v0, v199 offset:608
	ds_write_b16_d16_hi v0, v199 offset:880
	ds_write_b16 v0, v200 offset:2240
	ds_write_b16_d16_hi v0, v200 offset:2512
	ds_write_b16 v0, v201 offset:2784
	ds_write_b16_d16_hi v0, v201 offset:3056
	ds_write_b16 v0, v202 offset:4416
	ds_write_b16_d16_hi v0, v202 offset:4688
	ds_write_b16 v0, v203 offset:4960
	ds_write_b16_d16_hi v0, v203 offset:5232
	ds_write_b16 v0, v204 offset:6592
	ds_write_b16_d16_hi v0, v204 offset:6864
	ds_write_b16 v0, v205 offset:7136
	ds_write_b16_d16_hi v0, v205 offset:7408
	ds_write_b16 v0, v206 offset:8704
	ds_write_b16_d16_hi v0, v206 offset:8976
	ds_write_b16 v0, v207 offset:9248
	ds_write_b16_d16_hi v0, v207 offset:9520
	ds_write_b16 v0, v208 offset:10880
	ds_write_b16_d16_hi v0, v208 offset:11152
	ds_write_b16 v0, v209 offset:11424
	ds_write_b16_d16_hi v0, v209 offset:11696
	ds_write_b16 v0, v210 offset:13056
	ds_write_b16_d16_hi v0, v210 offset:13328
	ds_write_b16 v0, v211 offset:13600
	ds_write_b16_d16_hi v0, v211 offset:13872
	ds_write_b16 v0, v212 offset:15232
	ds_write_b16_d16_hi v0, v212 offset:15504
	ds_write_b16 v0, v213 offset:15776
	ds_write_b16_d16_hi v0, v213 offset:16048
	ds_write_b16 v0, v214 offset:8768
	ds_write_b16_d16_hi v0, v214 offset:9040
	ds_write_b16 v0, v215 offset:9312
	ds_write_b16_d16_hi v0, v215 offset:9584
	ds_write_b16 v0, v216 offset:10944
	ds_write_b16_d16_hi v0, v216 offset:11216
	ds_write_b16 v0, v217 offset:11488
	ds_write_b16_d16_hi v0, v217 offset:11760
	ds_write_b16 v0, v218 offset:13120
	ds_write_b16_d16_hi v0, v218 offset:13392
	ds_write_b16 v0, v219 offset:13664
	ds_write_b16_d16_hi v0, v219 offset:13936
	ds_write_b16 v0, v220 offset:15296
	ds_write_b16_d16_hi v0, v220 offset:15568
	ds_write_b16 v0, v221 offset:15840
	ds_write_b16_d16_hi v0, v221 offset:16112
	s_waitcnt lgkmcnt(0)
	s_barrier
	ds_read_b128 v[8:11], v1
	ds_read_b128 v[12:15], v1 offset:4352
	ds_read_b128 v[16:19], v1 offset:8704
	ds_read_b128 v[20:23], v1 offset:13056
	ds_read_b128 v[24:27], v1 offset:17408
	ds_read_b128 v[28:31], v1 offset:21760
	ds_read_b128 v[32:35], v1 offset:26112
	ds_read_b128 v[36:39], v1 offset:30464
	s_and_b64 exec, exec, s[44:45]
	s_add_u32 s42, s46, 0x0
	s_addc_u32 s43, s47, 0
	s_waitcnt lgkmcnt(7)
	global_store_dwordx4 v2, v[8:11], s[42:43]
	s_add_u32 s42, s46, 0x12400
	s_addc_u32 s43, s47, 0
	s_waitcnt lgkmcnt(6)
	global_store_dwordx4 v2, v[12:15], s[42:43]
	s_add_u32 s42, s46, 0x24800
	s_addc_u32 s43, s47, 0
	s_waitcnt lgkmcnt(5)
	global_store_dwordx4 v2, v[16:19], s[42:43]
	s_add_u32 s42, s46, 0x36c00
	s_addc_u32 s43, s47, 0
	s_waitcnt lgkmcnt(4)
	global_store_dwordx4 v2, v[20:23], s[42:43]
	s_add_u32 s42, s46, 0x92000
	s_addc_u32 s43, s47, 0
	s_waitcnt lgkmcnt(3)
	global_store_dwordx4 v2, v[24:27], s[42:43]
	s_add_u32 s42, s46, 0xa4400
	s_addc_u32 s43, s47, 0
	s_waitcnt lgkmcnt(2)
	global_store_dwordx4 v2, v[28:31], s[42:43]
	s_add_u32 s42, s46, 0xb6800
	s_addc_u32 s43, s47, 0
	s_waitcnt lgkmcnt(1)
	global_store_dwordx4 v2, v[32:35], s[42:43]
	s_add_u32 s42, s46, 0xc8c00
	s_addc_u32 s43, s47, 0
	s_waitcnt lgkmcnt(0)
	global_store_dwordx4 v2, v[36:39], s[42:43]
	s_mov_b64 exec, -1
	s_barrier
	ds_write_b16 v0, v222
	ds_write_b16_d16_hi v0, v222 offset:272
	ds_write_b16 v0, v223 offset:544
	ds_write_b16_d16_hi v0, v223 offset:816
	ds_write_b16 v0, v224 offset:2176
	ds_write_b16_d16_hi v0, v224 offset:2448
	ds_write_b16 v0, v225 offset:2720
	ds_write_b16_d16_hi v0, v225 offset:2992
	ds_write_b16 v0, v226 offset:4352
	ds_write_b16_d16_hi v0, v226 offset:4624
	ds_write_b16 v0, v227 offset:4896
	ds_write_b16_d16_hi v0, v227 offset:5168
	ds_write_b16 v0, v228 offset:6528
	ds_write_b16_d16_hi v0, v228 offset:6800
	ds_write_b16 v0, v229 offset:7072
	ds_write_b16_d16_hi v0, v229 offset:7344
	ds_write_b16 v0, v230 offset:64
	ds_write_b16_d16_hi v0, v230 offset:336
	ds_write_b16 v0, v231 offset:608
	ds_write_b16_d16_hi v0, v231 offset:880
	ds_write_b16 v0, v232 offset:2240
	ds_write_b16_d16_hi v0, v232 offset:2512
	ds_write_b16 v0, v233 offset:2784
	ds_write_b16_d16_hi v0, v233 offset:3056
	ds_write_b16 v0, v234 offset:4416
	ds_write_b16_d16_hi v0, v234 offset:4688
	ds_write_b16 v0, v235 offset:4960
	ds_write_b16_d16_hi v0, v235 offset:5232
	ds_write_b16 v0, v236 offset:6592
	ds_write_b16_d16_hi v0, v236 offset:6864
	ds_write_b16 v0, v237 offset:7136
	ds_write_b16_d16_hi v0, v237 offset:7408
	ds_write_b16 v0, v238 offset:8704
	ds_write_b16_d16_hi v0, v238 offset:8976
	ds_write_b16 v0, v239 offset:9248
	ds_write_b16_d16_hi v0, v239 offset:9520
	ds_write_b16 v0, v240 offset:10880
	ds_write_b16_d16_hi v0, v240 offset:11152
	ds_write_b16 v0, v241 offset:11424
	ds_write_b16_d16_hi v0, v241 offset:11696
	ds_write_b16 v0, v242 offset:13056
	ds_write_b16_d16_hi v0, v242 offset:13328
	ds_write_b16 v0, v243 offset:13600
	ds_write_b16_d16_hi v0, v243 offset:13872
	ds_write_b16 v0, v244 offset:15232
	ds_write_b16_d16_hi v0, v244 offset:15504
	ds_write_b16 v0, v245 offset:15776
	ds_write_b16_d16_hi v0, v245 offset:16048
	ds_write_b16 v0, v246 offset:8768
	ds_write_b16_d16_hi v0, v246 offset:9040
	ds_write_b16 v0, v247 offset:9312
	ds_write_b16_d16_hi v0, v247 offset:9584
	ds_write_b16 v0, v248 offset:10944
	ds_write_b16_d16_hi v0, v248 offset:11216
	ds_write_b16 v0, v249 offset:11488
	ds_write_b16_d16_hi v0, v249 offset:11760
	ds_write_b16 v0, v250 offset:13120
	ds_write_b16_d16_hi v0, v250 offset:13392
	ds_write_b16 v0, v251 offset:13664
	ds_write_b16_d16_hi v0, v251 offset:13936
	ds_write_b16 v0, v252 offset:15296
	ds_write_b16_d16_hi v0, v252 offset:15568
	ds_write_b16 v0, v253 offset:15840
	ds_write_b16_d16_hi v0, v253 offset:16112
	s_waitcnt lgkmcnt(0)
	s_barrier
	ds_read_b128 v[8:11], v1
	ds_read_b128 v[12:15], v1 offset:4352
	ds_read_b128 v[16:19], v1 offset:8704
	ds_read_b128 v[20:23], v1 offset:13056
	ds_read_b128 v[24:27], v1 offset:17408
	ds_read_b128 v[28:31], v1 offset:21760
	ds_read_b128 v[32:35], v1 offset:26112
	ds_read_b128 v[36:39], v1 offset:30464
	s_and_b64 exec, exec, s[44:45]
	s_add_u32 s42, s46, 0x49000
	s_addc_u32 s43, s47, 0
	s_waitcnt lgkmcnt(7)
	global_store_dwordx4 v2, v[8:11], s[42:43]
	s_add_u32 s42, s46, 0x5b400
	s_addc_u32 s43, s47, 0
	s_waitcnt lgkmcnt(6)
	global_store_dwordx4 v2, v[12:15], s[42:43]
	s_add_u32 s42, s46, 0x6d800
	s_addc_u32 s43, s47, 0
	s_waitcnt lgkmcnt(5)
	global_store_dwordx4 v2, v[16:19], s[42:43]
	s_add_u32 s42, s46, 0x7fc00
	s_addc_u32 s43, s47, 0
	s_waitcnt lgkmcnt(4)
	global_store_dwordx4 v2, v[20:23], s[42:43]
	s_add_u32 s42, s46, 0xdb000
	s_addc_u32 s43, s47, 0
	s_waitcnt lgkmcnt(3)
	global_store_dwordx4 v2, v[24:27], s[42:43]
	s_add_u32 s42, s46, 0xed400
	s_addc_u32 s43, s47, 0
	s_waitcnt lgkmcnt(2)
	global_store_dwordx4 v2, v[28:31], s[42:43]
	s_add_u32 s42, s46, 0xff800
	s_addc_u32 s43, s47, 0
	s_waitcnt lgkmcnt(1)
	global_store_dwordx4 v2, v[32:35], s[42:43]
	s_add_u32 s42, s46, 0x111c00
	s_addc_u32 s43, s47, 0
	s_waitcnt lgkmcnt(0)
	global_store_dwordx4 v2, v[36:39], s[42:43]
	s_mov_b64 exec, -1
	v_mov_b32_e32 v0, 0
	v_mov_b32_e32 v1, 0
	v_mov_b32_e32 v2, 0
	v_mov_b32_e32 v3, 0
	v_mov_b32_e32 v4, 0
	v_mov_b32_e32 v5, 0
	v_mov_b32_e32 v6, 0
	v_mov_b32_e32 v7, 0
	v_mov_b32_e32 v8, 0
	v_mov_b32_e32 v9, 0
	v_mov_b32_e32 v10, 0
	v_mov_b32_e32 v11, 0
	v_mov_b32_e32 v12, 0
	v_mov_b32_e32 v13, 0
	v_mov_b32_e32 v14, 0
	v_mov_b32_e32 v15, 0
	v_mov_b32_e32 v16, 0
	v_mov_b32_e32 v17, 0
	v_mov_b32_e32 v18, 0
	v_mov_b32_e32 v19, 0
	v_mov_b32_e32 v20, 0
	v_mov_b32_e32 v21, 0
	v_mov_b32_e32 v22, 0
	v_mov_b32_e32 v23, 0
	v_mov_b32_e32 v24, 0
	v_mov_b32_e32 v25, 0
	v_mov_b32_e32 v26, 0
	v_mov_b32_e32 v27, 0
	v_mov_b32_e32 v28, 0
	v_mov_b32_e32 v29, 0
	v_mov_b32_e32 v30, 0
	v_mov_b32_e32 v31, 0
	v_mov_b32_e32 v32, 0
	v_mov_b32_e32 v33, 0
	v_mov_b32_e32 v34, 0
	v_mov_b32_e32 v35, 0
	v_mov_b32_e32 v36, 0
	v_mov_b32_e32 v37, 0
	v_mov_b32_e32 v38, 0
	v_mov_b32_e32 v39, 0
.Lv5_a_2:
	v_readfirstlane_b32 s42, v180
	v_readfirstlane_b32 s43, v181
	v_readfirstlane_b32 s44, v178
	v_readfirstlane_b32 s45, v179
	v_lshrrev_b32_e32 v198, 3, v182
	v_and_b32_e32 v199, 7, v182
	v_lshlrev_b32_e32 v198, 11, v198
	v_lshl_or_b32 v190, v199, 4, v198
	s_lshl_b32 s41, s33, 8
	s_sub_u32 s42, s42, s41
	s_subb_u32 s43, s43, 0
	s_sub_u32 s44, s44, s41
	s_subb_u32 s45, s45, 0
	s_add_u32 s42, s42, 0x2957980
	s_addc_u32 s43, s43, 0
	s_add_u32 s44, s44, 0x80
	s_addc_u32 s45, s45, 0
	v_add_u32_e32 v191, 0x10000, v190
	v_add_u32_e32 v192, 0x20000, v190
	v_add_u32_e32 v193, 0x30000, v190
	v_add_u32_e32 v194, 0x40000, v190
	v_add_u32_e32 v195, 0x50000, v190
	v_add_u32_e32 v196, 0x60000, v190
	v_add_u32_e32 v197, 0x70000, v190
	s_waitcnt lgkmcnt(0)
	s_barrier
	s_cmp_eq_u32 s48, 0
	s_cbranch_scc1 .Lv5_b_2
	s_waitcnt vmcnt(16)
	s_mov_b32 s48, 0
	s_branch .Lv5_c_2

.Lv5_c_2:
	ds_write_b128 v189, v[164:167]
	ds_write_b128 v189, v[128:131] offset:4608
	ds_write_b128 v189, v[132:135] offset:9216
	ds_write_b128 v189, v[136:139] offset:13824
	ds_write_b128 v189, v[144:147] offset:18432
	ds_write_b128 v189, v[148:151] offset:23040
	ds_write_b128 v189, v[152:155] offset:27648
	ds_write_b128 v189, v[156:159] offset:32256
	ds_write_b128 v189, v[140:143] offset:36864
	ds_write_b128 v189, v[160:163] offset:41472
	ds_write_b128 v189, v[168:171] offset:46080
	ds_write_b128 v189, v[172:175] offset:50688
	global_load_dwordx4 v[164:167], v190, s[42:43]
	global_load_dwordx4 v[128:131], v191, s[42:43]
	global_load_dwordx4 v[132:135], v192, s[42:43]
	global_load_dwordx4 v[136:139], v193, s[42:43]
	global_load_dwordx4 v[144:147], v194, s[42:43]
	global_load_dwordx4 v[148:151], v195, s[42:43]
	s_waitcnt lgkmcnt(0)
	s_barrier
.LBB0_1284:
	ds_read_b128 v[216:219], v176 offset:36864
	ds_read_b128 v[200:203], v188
	ds_read_b128 v[220:223], v176 offset:41472
	ds_read_b128 v[204:207], v188 offset:4608
	ds_read_b128 v[208:211], v188 offset:9216
	ds_read_b128 v[212:215], v187
	s_waitcnt lgkmcnt(4)
	v_mfma_f32_32x32x16_bf16 v[112:127], v[200:203], v[216:219], v[112:127]
	ds_read_b128 v[240:243], v176 offset:36896
	global_load_dwordx4 v[140:143], v190, s[44:45]
	s_waitcnt lgkmcnt(4)
	v_mfma_f32_32x32x16_bf16 v[96:111], v[200:203], v[220:223], v[96:111]
	ds_read_b128 v[224:227], v188 offset:32
	global_load_dwordx4 v[160:163], v191, s[44:45]
	s_waitcnt lgkmcnt(4)
	v_mfma_f32_32x32x16_bf16 v[80:95], v[204:207], v[216:219], v[80:95]
	ds_read_b128 v[244:247], v176 offset:41504
	global_load_dwordx4 v[168:171], v192, s[44:45]
	s_waitcnt lgkmcnt(5)
	v_mfma_f32_32x32x16_bf16 v[64:79], v[204:207], v[220:223], v[64:79]
	ds_read_b128 v[228:231], v188 offset:4640
	global_load_dwordx4 v[172:175], v193, s[44:45]
	s_waitcnt lgkmcnt(5)
	v_mfma_f32_32x32x16_bf16 v[48:63], v[208:211], v[216:219], v[48:63]
	ds_read_b128 v[232:235], v188 offset:9248
	global_load_dwordx4 v[152:155], v196, s[42:43]
	s_waitcnt lgkmcnt(6)
	v_mfma_f32_32x32x16_bf16 v[32:47], v[208:211], v[220:223], v[32:47]
	ds_read_b128 v[236:239], v187 offset:32
	global_load_dwordx4 v[156:159], v197, s[42:43]
	s_add_u32 s42, s42, 0x80
	s_addc_u32 s43, s43, 0
	s_add_u32 s44, s44, 0x80
	s_addc_u32 s45, s45, 0
	s_add_u32 s16, s16, 0x80
	s_waitcnt lgkmcnt(6)
	v_mfma_f32_32x32x16_bf16 v[16:31], v[212:215], v[216:219], v[16:31]
	s_waitcnt lgkmcnt(6)
	v_mfma_f32_32x32x16_bf16 v[0:15], v[212:215], v[220:223], v[0:15]
	s_waitcnt lgkmcnt(4)
	v_mfma_f32_32x32x16_bf16 v[112:127], v[224:227], v[240:243], v[112:127]
	ds_read_b128 v[200:203], v188 offset:64
	s_waitcnt lgkmcnt(4)
	v_mfma_f32_32x32x16_bf16 v[96:111], v[224:227], v[244:247], v[96:111]
	ds_read_b128 v[204:207], v188 offset:4672
	s_waitcnt lgkmcnt(4)
	v_mfma_f32_32x32x16_bf16 v[80:95], v[228:231], v[240:243], v[80:95]
	ds_read_b128 v[208:211], v188 offset:9280
	s_waitcnt lgkmcnt(5)
	v_mfma_f32_32x32x16_bf16 v[64:79], v[228:231], v[244:247], v[64:79]
	ds_read_b128 v[212:215], v187 offset:64
	s_waitcnt lgkmcnt(5)
	v_mfma_f32_32x32x16_bf16 v[48:63], v[232:235], v[240:243], v[48:63]
	ds_read_b128 v[216:219], v176 offset:36928
	s_waitcnt lgkmcnt(6)
	v_mfma_f32_32x32x16_bf16 v[32:47], v[232:235], v[244:247], v[32:47]
	ds_read_b128 v[220:223], v176 offset:41536
	s_waitcnt lgkmcnt(6)
	v_mfma_f32_32x32x16_bf16 v[16:31], v[236:239], v[240:243], v[16:31]
	s_waitcnt lgkmcnt(6)
	v_mfma_f32_32x32x16_bf16 v[0:15], v[236:239], v[244:247], v[0:15]
	s_waitcnt lgkmcnt(1)
	v_mfma_f32_32x32x16_bf16 v[112:127], v[200:203], v[216:219], v[112:127]
	ds_read_b128 v[224:227], v188 offset:96
	s_waitcnt lgkmcnt(1)
	v_mfma_f32_32x32x16_bf16 v[96:111], v[200:203], v[220:223], v[96:111]
	ds_read_b128 v[228:231], v188 offset:4704
	s_waitcnt lgkmcnt(3)
	v_mfma_f32_32x32x16_bf16 v[80:95], v[204:207], v[216:219], v[80:95]
	ds_read_b128 v[232:235], v188 offset:9312
	s_waitcnt lgkmcnt(3)
	v_mfma_f32_32x32x16_bf16 v[64:79], v[204:207], v[220:223], v[64:79]
	ds_read_b128 v[236:239], v187 offset:96
	s_waitcnt lgkmcnt(5)
	v_mfma_f32_32x32x16_bf16 v[48:63], v[208:211], v[216:219], v[48:63]
	ds_read_b128 v[240:243], v176 offset:36960
	s_waitcnt lgkmcnt(5)
	v_mfma_f32_32x32x16_bf16 v[32:47], v[208:211], v[220:223], v[32:47]
	ds_read_b128 v[244:247], v176 offset:41568
	s_waitcnt lgkmcnt(7)
	v_mfma_f32_32x32x16_bf16 v[16:31], v[212:215], v[216:219], v[16:31]
	s_waitcnt lgkmcnt(6)
	v_mfma_f32_32x32x16_bf16 v[0:15], v[212:215], v[220:223], v[0:15]
	s_waitcnt lgkmcnt(0)
	s_barrier
	s_waitcnt vmcnt(6)
	s_waitcnt lgkmcnt(1)
	v_mfma_f32_32x32x16_bf16 v[112:127], v[224:227], v[240:243], v[112:127]
	ds_write_b128 v189, v[164:167]
	ds_write_b128 v189, v[128:131] offset:4608
	s_waitcnt lgkmcnt(2)
	v_mfma_f32_32x32x16_bf16 v[96:111], v[224:227], v[244:247], v[96:111]
	ds_write_b128 v189, v[132:135] offset:9216
	global_load_dwordx4 v[164:167], v190, s[42:43]
	s_waitcnt lgkmcnt(4)
	v_mfma_f32_32x32x16_bf16 v[80:95], v[228:231], v[240:243], v[80:95]
	ds_write_b128 v189, v[136:139] offset:13824
	ds_write_b128 v189, v[144:147] offset:18432
	global_load_dwordx4 v[128:131], v191, s[42:43]
	s_waitcnt lgkmcnt(5)
	v_mfma_f32_32x32x16_bf16 v[64:79], v[228:231], v[244:247], v[64:79]
	ds_write_b128 v189, v[148:151] offset:23040
	global_load_dwordx4 v[132:135], v192, s[42:43]
	s_waitcnt lgkmcnt(7)
	v_mfma_f32_32x32x16_bf16 v[48:63], v[232:235], v[240:243], v[48:63]
	s_waitcnt vmcnt(8)
	ds_write_b128 v189, v[140:143] offset:36864
	s_waitcnt vmcnt(7)
	ds_write_b128 v189, v[160:163] offset:41472
	global_load_dwordx4 v[136:139], v193, s[42:43]
	s_waitcnt lgkmcnt(8)
	v_mfma_f32_32x32x16_bf16 v[32:47], v[232:235], v[244:247], v[32:47]
	s_waitcnt vmcnt(7)
	ds_write_b128 v189, v[168:171] offset:46080
	global_load_dwordx4 v[144:147], v194, s[42:43]
	s_waitcnt lgkmcnt(10)
	v_mfma_f32_32x32x16_bf16 v[16:31], v[236:239], v[240:243], v[16:31]
	s_waitcnt vmcnt(7)
	ds_write_b128 v189, v[172:175] offset:50688
	s_waitcnt vmcnt(6)
	ds_write_b128 v189, v[152:155] offset:27648
	global_load_dwordx4 v[148:151], v195, s[42:43]
	s_waitcnt lgkmcnt(11)
	v_mfma_f32_32x32x16_bf16 v[0:15], v[236:239], v[244:247], v[0:15]
	s_waitcnt vmcnt(6)
	ds_write_b128 v189, v[156:159] offset:32256
	s_waitcnt lgkmcnt(0)
	s_barrier
	s_cmpk_lg_i32 s16, 0x780
	s_cbranch_scc1 .LBB0_1284
	ds_read_b128 v[216:219], v176 offset:36864
	ds_read_b128 v[200:203], v188
	ds_read_b128 v[220:223], v176 offset:41472
	ds_read_b128 v[204:207], v188 offset:4608
	ds_read_b128 v[208:211], v188 offset:9216
	ds_read_b128 v[212:215], v187
	s_waitcnt lgkmcnt(4)
	v_mfma_f32_32x32x16_bf16 v[112:127], v[200:203], v[216:219], v[112:127]
	ds_read_b128 v[240:243], v176 offset:36896
	s_waitcnt lgkmcnt(4)
	v_mfma_f32_32x32x16_bf16 v[96:111], v[200:203], v[220:223], v[96:111]
	ds_read_b128 v[224:227], v188 offset:32
	s_waitcnt lgkmcnt(4)
	v_mfma_f32_32x32x16_bf16 v[80:95], v[204:207], v[216:219], v[80:95]
	ds_read_b128 v[244:247], v176 offset:41504
	s_waitcnt lgkmcnt(5)
	v_mfma_f32_32x32x16_bf16 v[64:79], v[204:207], v[220:223], v[64:79]
	ds_read_b128 v[228:231], v188 offset:4640
	s_waitcnt lgkmcnt(5)
	v_mfma_f32_32x32x16_bf16 v[48:63], v[208:211], v[216:219], v[48:63]
	ds_read_b128 v[232:235], v188 offset:9248
	s_waitcnt lgkmcnt(6)
	v_mfma_f32_32x32x16_bf16 v[32:47], v[208:211], v[220:223], v[32:47]
	ds_read_b128 v[236:239], v187 offset:32
	s_waitcnt lgkmcnt(6)
	v_mfma_f32_32x32x16_bf16 v[16:31], v[212:215], v[216:219], v[16:31]
	s_waitcnt lgkmcnt(6)
	v_mfma_f32_32x32x16_bf16 v[0:15], v[212:215], v[220:223], v[0:15]
	s_waitcnt lgkmcnt(4)
	v_mfma_f32_32x32x16_bf16 v[112:127], v[224:227], v[240:243], v[112:127]
	ds_read_b128 v[200:203], v188 offset:64
	s_waitcnt lgkmcnt(4)
	v_mfma_f32_32x32x16_bf16 v[96:111], v[224:227], v[244:247], v[96:111]
	ds_read_b128 v[204:207], v188 offset:4672
	s_waitcnt lgkmcnt(4)
	v_mfma_f32_32x32x16_bf16 v[80:95], v[228:231], v[240:243], v[80:95]
	ds_read_b128 v[208:211], v188 offset:9280
	s_waitcnt lgkmcnt(5)
	v_mfma_f32_32x32x16_bf16 v[64:79], v[228:231], v[244:247], v[64:79]
	ds_read_b128 v[212:215], v187 offset:64
	s_waitcnt lgkmcnt(5)
	v_mfma_f32_32x32x16_bf16 v[48:63], v[232:235], v[240:243], v[48:63]
	ds_read_b128 v[216:219], v176 offset:36928
	s_waitcnt lgkmcnt(6)
	v_mfma_f32_32x32x16_bf16 v[32:47], v[232:235], v[244:247], v[32:47]
	ds_read_b128 v[220:223], v176 offset:41536
	s_waitcnt lgkmcnt(6)
	v_mfma_f32_32x32x16_bf16 v[16:31], v[236:239], v[240:243], v[16:31]
	s_waitcnt lgkmcnt(6)
	v_mfma_f32_32x32x16_bf16 v[0:15], v[236:239], v[244:247], v[0:15]
	s_waitcnt lgkmcnt(1)
	v_mfma_f32_32x32x16_bf16 v[112:127], v[200:203], v[216:219], v[112:127]
	ds_read_b128 v[224:227], v188 offset:96
	s_waitcnt lgkmcnt(1)
	v_mfma_f32_32x32x16_bf16 v[96:111], v[200:203], v[220:223], v[96:111]
	ds_read_b128 v[228:231], v188 offset:4704
	s_waitcnt lgkmcnt(3)
	v_mfma_f32_32x32x16_bf16 v[80:95], v[204:207], v[216:219], v[80:95]
	ds_read_b128 v[232:235], v188 offset:9312
	s_waitcnt lgkmcnt(3)
	v_mfma_f32_32x32x16_bf16 v[64:79], v[204:207], v[220:223], v[64:79]
	ds_read_b128 v[236:239], v187 offset:96
	s_waitcnt lgkmcnt(5)
	v_mfma_f32_32x32x16_bf16 v[48:63], v[208:211], v[216:219], v[48:63]
	ds_read_b128 v[240:243], v176 offset:36960
	s_waitcnt lgkmcnt(5)
	v_mfma_f32_32x32x16_bf16 v[32:47], v[208:211], v[220:223], v[32:47]
	ds_read_b128 v[244:247], v176 offset:41568
	s_waitcnt lgkmcnt(7)
	v_mfma_f32_32x32x16_bf16 v[16:31], v[212:215], v[216:219], v[16:31]
	s_waitcnt lgkmcnt(6)
	v_mfma_f32_32x32x16_bf16 v[0:15], v[212:215], v[220:223], v[0:15]
	s_waitcnt lgkmcnt(1)
	v_mfma_f32_32x32x16_bf16 v[112:127], v[224:227], v[240:243], v[112:127]
	s_waitcnt lgkmcnt(0)
	v_mfma_f32_32x32x16_bf16 v[96:111], v[224:227], v[244:247], v[96:111]
	s_waitcnt lgkmcnt(1)
	v_mfma_f32_32x32x16_bf16 v[80:95], v[228:231], v[240:243], v[80:95]
	s_waitcnt lgkmcnt(0)
	v_mfma_f32_32x32x16_bf16 v[64:79], v[228:231], v[244:247], v[64:79]
	s_waitcnt lgkmcnt(1)
	v_mfma_f32_32x32x16_bf16 v[48:63], v[232:235], v[240:243], v[48:63]
	s_waitcnt lgkmcnt(0)
	v_mfma_f32_32x32x16_bf16 v[32:47], v[232:235], v[244:247], v[32:47]
	s_waitcnt lgkmcnt(1)
	v_mfma_f32_32x32x16_bf16 v[16:31], v[236:239], v[240:243], v[16:31]
	s_waitcnt lgkmcnt(0)
	v_mfma_f32_32x32x16_bf16 v[0:15], v[236:239], v[244:247], v[0:15]
	s_waitcnt vmcnt(0)
	s_mul_i32 s41, s12, 0x1240
	s_add_u32 s46, s30, s41
	s_addc_u32 s47, s31, 0
	s_lshl_b32 s41, s8, 1
	s_add_u32 s46, s46, s41
	s_addc_u32 s47, s47, 0
	s_add_u32 s46, s46, 0x7157900
	s_addc_u32 s47, s47, 0
	s_cmp_eq_u32 s8, 0x900
	s_cselect_b32 s48, 2, 1
	v_cvt_pk_bf16_f32 v190, v112, v113
	v_cvt_pk_bf16_f32 v191, v114, v115
	v_cvt_pk_bf16_f32 v192, v116, v117
	v_cvt_pk_bf16_f32 v193, v118, v119
	v_cvt_pk_bf16_f32 v194, v120, v121
	v_cvt_pk_bf16_f32 v195, v122, v123
	v_cvt_pk_bf16_f32 v196, v124, v125
	v_cvt_pk_bf16_f32 v197, v126, v127
	v_cvt_pk_bf16_f32 v198, v96, v97
	v_cvt_pk_bf16_f32 v199, v98, v99
	v_cvt_pk_bf16_f32 v200, v100, v101
	v_cvt_pk_bf16_f32 v201, v102, v103
	v_cvt_pk_bf16_f32 v202, v104, v105
	v_cvt_pk_bf16_f32 v203, v106, v107
	v_cvt_pk_bf16_f32 v204, v108, v109
	v_cvt_pk_bf16_f32 v205, v110, v111
	v_cvt_pk_bf16_f32 v206, v80, v81
	v_cvt_pk_bf16_f32 v207, v82, v83
	v_cvt_pk_bf16_f32 v208, v84, v85
	v_cvt_pk_bf16_f32 v209, v86, v87
	v_cvt_pk_bf16_f32 v210, v88, v89
	v_cvt_pk_bf16_f32 v211, v90, v91
	v_cvt_pk_bf16_f32 v212, v92, v93
	v_cvt_pk_bf16_f32 v213, v94, v95
	v_cvt_pk_bf16_f32 v214, v64, v65
	v_cvt_pk_bf16_f32 v215, v66, v67
	v_cvt_pk_bf16_f32 v216, v68, v69
	v_cvt_pk_bf16_f32 v217, v70, v71
	v_cvt_pk_bf16_f32 v218, v72, v73
	v_cvt_pk_bf16_f32 v219, v74, v75
	v_cvt_pk_bf16_f32 v220, v76, v77
	v_cvt_pk_bf16_f32 v221, v78, v79
	v_cvt_pk_bf16_f32 v222, v48, v49
	v_cvt_pk_bf16_f32 v223, v50, v51
	v_cvt_pk_bf16_f32 v224, v52, v53
	v_cvt_pk_bf16_f32 v225, v54, v55
	v_cvt_pk_bf16_f32 v226, v56, v57
	v_cvt_pk_bf16_f32 v227, v58, v59
	v_cvt_pk_bf16_f32 v228, v60, v61
	v_cvt_pk_bf16_f32 v229, v62, v63
	v_cvt_pk_bf16_f32 v230, v32, v33
	v_cvt_pk_bf16_f32 v231, v34, v35
	v_cvt_pk_bf16_f32 v232, v36, v37
	v_cvt_pk_bf16_f32 v233, v38, v39
	v_cvt_pk_bf16_f32 v234, v40, v41
	v_cvt_pk_bf16_f32 v235, v42, v43
	v_cvt_pk_bf16_f32 v236, v44, v45
	v_cvt_pk_bf16_f32 v237, v46, v47
	v_cvt_pk_bf16_f32 v238, v16, v17
	v_cvt_pk_bf16_f32 v239, v18, v19
	v_cvt_pk_bf16_f32 v240, v20, v21
	v_cvt_pk_bf16_f32 v241, v22, v23
	v_cvt_pk_bf16_f32 v242, v24, v25
	v_cvt_pk_bf16_f32 v243, v26, v27
	v_cvt_pk_bf16_f32 v244, v28, v29
	v_cvt_pk_bf16_f32 v245, v30, v31
	v_cvt_pk_bf16_f32 v246, v0, v1
	v_cvt_pk_bf16_f32 v247, v2, v3
	v_cvt_pk_bf16_f32 v248, v4, v5
	v_cvt_pk_bf16_f32 v249, v6, v7
	v_cvt_pk_bf16_f32 v250, v8, v9
	v_cvt_pk_bf16_f32 v251, v10, v11
	v_cvt_pk_bf16_f32 v252, v12, v13
	v_cvt_pk_bf16_f32 v253, v14, v15
	s_branch .LBB0_1281
